# DMA staging 4/4 rebalance in 12 K-loops + hand-written packed-f32 SwiGLU epilogue in FFN1-up + sc1 write-through dwordx4 stores in P0-P2
# speedup vs baseline: 1.0052x; 1.0018x over previous
; #define LAS __attribute__((address_space(3)))
; __device__ __forceinline__ unsigned cvt_pk_bf16(float lo, float hi) { unsigned r; asm("v_cvt_pk_bf16_f32 %0, %1, %2" : "=v"(r) : "v"(lo), "v"(hi)); return r; }
; #define LDS_WAIT() asm volatile("s_waitcnt lgkmcnt(0)" ::: "memory")
; __device__ __forceinline__ void p0_task(const float* W, int N, const float* gk, bf16_t* WT, int ldt, int k0, int n0, int nd0, LAS unsigned char* stg, int lane) {
;     ...
; #pragma unroll
;     for (int j = 0; j < 2; ++j) {
; #pragma unroll
;         for (int kb = 0; kb < 8; ++kb) {
;             u32x4 o; o.x = cvt_pk_bf16(v[8 * kb][j], v[8 * kb + 1][j]); o.y = cvt_pk_bf16(v[8 * kb + 2][j], v[8 * kb + 3][j]); o.z = cvt_pk_bf16(v[8 * kb + 4][j], v[8 * kb + 5][j]); o.w = cvt_pk_bf16(v[8 * kb + 6][j], v[8 * kb + 7][j]);
;             *(LAS u32x4*)(stg + lane * STG_PITCH + kb * 16) = o;
;         }
;         LDS_WAIT(); asm volatile("" ::: "memory");
; #pragma unroll
;         for (int it = 0; it < 8; ++it) {
;             const int rr = 8 * it + (lane >> 3), kb = lane & 7;
;             const u32x4 o = *(const LAS u32x4*)(stg + rr * STG_PITCH + kb * 16);
;             *(u32x4*)(WT + (size_t)(nd0 + 2 * rr + j) * ldt + k0 + 8 * kb) = o;
;         }
;         LDS_WAIT(); asm volatile("" ::: "memory");
;     }
.LBB0_34:
	s_waitcnt vmcnt(3)
	v_cvt_pk_bf16_f32 v146, v132, v12
	v_cvt_pk_bf16_f32 v147, v8, v10
	v_cvt_pk_bf16_f32 v148, v6, v20
	v_cvt_pk_bf16_f32 v149, v16, v18
	ds_write_b128 v144, v[146:149]
	v_cvt_pk_bf16_f32 v146, v14, v28
	v_cvt_pk_bf16_f32 v147, v24, v26
	v_cvt_pk_bf16_f32 v148, v22, v36
	v_cvt_pk_bf16_f32 v149, v32, v34
	ds_write_b128 v144, v[146:149] offset:16
	v_cvt_pk_bf16_f32 v146, v30, v44
	v_cvt_pk_bf16_f32 v147, v40, v42
	v_cvt_pk_bf16_f32 v148, v38, v52
	v_cvt_pk_bf16_f32 v149, v48, v50
	s_lshl_b32 s4, s75, 8
	ds_write_b128 v144, v[146:149] offset:32
	v_cvt_pk_bf16_f32 v146, v46, v60
	v_cvt_pk_bf16_f32 v147, v56, v58
	v_cvt_pk_bf16_f32 v148, v54, v68
	v_cvt_pk_bf16_f32 v149, v64, v66
	s_or_b32 s4, s4, s74
	ds_write_b128 v144, v[146:149] offset:48
	v_cvt_pk_bf16_f32 v146, v62, v76
	v_cvt_pk_bf16_f32 v147, v72, v74
	v_cvt_pk_bf16_f32 v148, v70, v84
	v_cvt_pk_bf16_f32 v149, v80, v82
	s_and_b64 s[12:13], s[12:13], exec
	ds_write_b128 v144, v[146:149] offset:64
	v_cvt_pk_bf16_f32 v146, v78, v92
	v_cvt_pk_bf16_f32 v147, v88, v90
	v_cvt_pk_bf16_f32 v148, v86, v100
	v_cvt_pk_bf16_f32 v149, v96, v98
	s_cselect_b32 s4, s68, s4
	s_lshl_b64 s[12:13], s[16:17], 1
	ds_write_b128 v144, v[146:149] offset:80
	v_cvt_pk_bf16_f32 v146, v94, v108
	v_cvt_pk_bf16_f32 v147, v104, v106
	v_cvt_pk_bf16_f32 v148, v102, v116
	v_cvt_pk_bf16_f32 v149, v112, v114
	s_add_u32 s12, s14, s12
	ds_write_b128 v144, v[146:149] offset:96
	v_cvt_pk_bf16_f32 v146, v110, v124
	v_cvt_pk_bf16_f32 v147, v120, v122
	s_waitcnt vmcnt(2)
	v_cvt_pk_bf16_f32 v148, v118, v130
	s_waitcnt vmcnt(0)
	v_cvt_pk_bf16_f32 v149, v126, v128
	ds_write_b128 v144, v[146:149] offset:112
	s_addc_u32 s13, s15, s13
	s_waitcnt lgkmcnt(0)
	v_or_b32_e32 v6, s4, v136
	v_lshl_add_u64 v[134:135], s[12:13], 0, v[2:3]
	v_mad_u64_u32 v[150:151], s[12:13], v6, s35, 0
	ds_read_b128 v[146:149], v145
	s_ashr_i32 s12, s4, 31
	s_mul_i32 s12, s12, s35
	v_add_u32_e32 v151, s12, v151
	v_lshl_add_u64 v[154:155], v[150:151], 1, v[134:135]
	ds_read_b128 v[150:153], v145 offset:1152
	v_or_b32_e32 v6, s4, v137
	s_waitcnt lgkmcnt(1)
	global_store_dwordx4 v[154:155], v[146:149], off sc1
	v_cvt_pk_bf16_f32 v8, v133, v13
	v_cvt_pk_bf16_f32 v9, v9, v11
	v_cvt_pk_bf16_f32 v10, v7, v21
	v_cvt_pk_bf16_f32 v11, v17, v19
	v_cvt_pk_bf16_f32 v7, v25, v27
	s_nop 1
	v_mad_u64_u32 v[146:147], s[14:15], v6, s35, 0
	v_add_u32_e32 v147, s12, v147
	v_lshl_add_u64 v[146:147], v[146:147], 1, v[134:135]
	s_waitcnt lgkmcnt(0)
	global_store_dwordx4 v[146:147], v[150:153], off sc1
	ds_read_b128 v[146:149], v145 offset:2304
	v_or_b32_e32 v6, s4, v138
	v_mad_u64_u32 v[150:151], s[14:15], v6, s35, 0
	v_add_u32_e32 v151, s12, v151
	v_lshl_add_u64 v[154:155], v[150:151], 1, v[134:135]
	ds_read_b128 v[150:153], v145 offset:3456
	v_or_b32_e32 v6, s4, v139
	s_waitcnt lgkmcnt(1)
	global_store_dwordx4 v[154:155], v[146:149], off sc1
	s_add_i32 s34, s34, 1
	s_nop 0
	v_mad_u64_u32 v[146:147], s[14:15], v6, s35, 0
	v_add_u32_e32 v147, s12, v147
	v_lshl_add_u64 v[146:147], v[146:147], 1, v[134:135]
	s_waitcnt lgkmcnt(0)
	global_store_dwordx4 v[146:147], v[150:153], off sc1
	ds_read_b128 v[146:149], v145 offset:4608
	v_or_b32_e32 v6, s4, v140
	v_mad_u64_u32 v[150:151], s[14:15], v6, s35, 0
	v_add_u32_e32 v151, s12, v151
	v_lshl_add_u64 v[154:155], v[150:151], 1, v[134:135]
	ds_read_b128 v[150:153], v145 offset:5760
	v_or_b32_e32 v6, s4, v141
	s_waitcnt lgkmcnt(1)
	global_store_dwordx4 v[154:155], v[146:149], off sc1
	s_nop 1
	v_mad_u64_u32 v[146:147], s[14:15], v6, s35, 0
	v_add_u32_e32 v147, s12, v147
	v_lshl_add_u64 v[146:147], v[146:147], 1, v[134:135]
	s_waitcnt lgkmcnt(0)
	global_store_dwordx4 v[146:147], v[150:153], off sc1
	ds_read_b128 v[146:149], v145 offset:6912
	v_or_b32_e32 v6, s4, v142
	v_mad_u64_u32 v[150:151], s[14:15], v6, s35, 0
	v_add_u32_e32 v151, s12, v151
	v_lshl_add_u64 v[154:155], v[150:151], 1, v[134:135]
	ds_read_b128 v[150:153], v145 offset:8064
	v_or_b32_e32 v6, s4, v143
	s_waitcnt lgkmcnt(1)
; #define LAS __attribute__((address_space(3)))
; __device__ __forceinline__ unsigned cvt_pk_bf16(float lo, float hi) { unsigned r; asm("v_cvt_pk_bf16_f32 %0, %1, %2" : "=v"(r) : "v"(lo), "v"(hi)); return r; }
; #define LDS_WAIT() asm volatile("s_waitcnt lgkmcnt(0)" ::: "memory")
; __device__ __forceinline__ void p0_task(const float* W, int N, const float* gk, bf16_t* WT, int ldt, int k0, int n0, int nd0, LAS unsigned char* stg, int lane) {
;     ...
; #pragma unroll
;     for (int j = 0; j < 2; ++j) {
; #pragma unroll
;         for (int kb = 0; kb < 8; ++kb) {
;             u32x4 o; o.x = cvt_pk_bf16(v[8 * kb][j], v[8 * kb + 1][j]); o.y = cvt_pk_bf16(v[8 * kb + 2][j], v[8 * kb + 3][j]); o.z = cvt_pk_bf16(v[8 * kb + 4][j], v[8 * kb + 5][j]); o.w = cvt_pk_bf16(v[8 * kb + 6][j], v[8 * kb + 7][j]);
;             *(LAS u32x4*)(stg + lane * STG_PITCH + kb * 16) = o;
;         }
;         LDS_WAIT(); asm volatile("" ::: "memory");
; #pragma unroll
;         for (int it = 0; it < 8; ++it) {
;             const int rr = 8 * it + (lane >> 3), kb = lane & 7;
;             const u32x4 o = *(const LAS u32x4*)(stg + rr * STG_PITCH + kb * 16);
;             *(u32x4*)(WT + (size_t)(nd0 + 2 * rr + j) * ldt + k0 + 8 * kb) = o;
;         }
;         LDS_WAIT(); asm volatile("" ::: "memory");
;     }
	global_store_dwordx4 v[154:155], v[146:149], off sc1
	s_or_b32 s4, s4, 1
	s_cmp_lt_i32 s34, s33
	v_mad_u64_u32 v[146:147], s[14:15], v6, s35, 0
	v_add_u32_e32 v147, s12, v147
	v_lshl_add_u64 v[146:147], v[146:147], 1, v[134:135]
	s_waitcnt lgkmcnt(0)
	global_store_dwordx4 v[146:147], v[150:153], off sc1
	s_waitcnt lgkmcnt(0)
	ds_write_b128 v144, v[8:11]
	v_cvt_pk_bf16_f32 v6, v15, v29
	v_cvt_pk_bf16_f32 v8, v23, v37
	v_cvt_pk_bf16_f32 v9, v33, v35
	ds_write_b128 v144, v[6:9] offset:16
	v_cvt_pk_bf16_f32 v6, v31, v45
	v_cvt_pk_bf16_f32 v7, v41, v43
	v_cvt_pk_bf16_f32 v8, v39, v53
	v_cvt_pk_bf16_f32 v9, v49, v51
	ds_write_b128 v144, v[6:9] offset:32
	v_cvt_pk_bf16_f32 v6, v47, v61
	v_cvt_pk_bf16_f32 v7, v57, v59
	v_cvt_pk_bf16_f32 v8, v55, v69
	v_cvt_pk_bf16_f32 v9, v65, v67
	ds_write_b128 v144, v[6:9] offset:48
	v_cvt_pk_bf16_f32 v6, v63, v77
	v_cvt_pk_bf16_f32 v7, v73, v75
	v_cvt_pk_bf16_f32 v8, v71, v85
	v_cvt_pk_bf16_f32 v9, v81, v83
	ds_write_b128 v144, v[6:9] offset:64
	v_cvt_pk_bf16_f32 v6, v79, v93
	v_cvt_pk_bf16_f32 v7, v89, v91
	v_cvt_pk_bf16_f32 v8, v87, v101
	v_cvt_pk_bf16_f32 v9, v97, v99
	ds_write_b128 v144, v[6:9] offset:80
	v_cvt_pk_bf16_f32 v6, v95, v109
	v_cvt_pk_bf16_f32 v7, v105, v107
	v_cvt_pk_bf16_f32 v8, v103, v117
	v_cvt_pk_bf16_f32 v9, v113, v115
	ds_write_b128 v144, v[6:9] offset:96
	v_cvt_pk_bf16_f32 v6, v111, v125
	v_cvt_pk_bf16_f32 v7, v121, v123
	v_cvt_pk_bf16_f32 v8, v119, v131
	v_cvt_pk_bf16_f32 v9, v127, v129
	ds_write_b128 v144, v[6:9] offset:112
	s_waitcnt lgkmcnt(0)
	ds_read_b128 v[6:9], v145
	v_or_b32_e32 v10, s4, v136
	v_mad_u64_u32 v[10:11], s[14:15], v10, s35, 0
	v_add_u32_e32 v11, s12, v11
	v_lshl_add_u64 v[14:15], v[10:11], 1, v[134:135]
	ds_read_b128 v[10:13], v145 offset:1152
	s_waitcnt lgkmcnt(1)
	global_store_dwordx4 v[14:15], v[6:9], off sc1
	s_nop 1
	v_or_b32_e32 v6, s4, v137
	v_mad_u64_u32 v[6:7], s[14:15], v6, s35, 0
	v_add_u32_e32 v7, s12, v7
	v_lshl_add_u64 v[6:7], v[6:7], 1, v[134:135]
	s_waitcnt lgkmcnt(0)
	global_store_dwordx4 v[6:7], v[10:13], off sc1
	ds_read_b128 v[6:9], v145 offset:2304
	s_nop 0
	v_or_b32_e32 v10, s4, v138
	v_mad_u64_u32 v[10:11], s[14:15], v10, s35, 0
	v_add_u32_e32 v11, s12, v11
	v_lshl_add_u64 v[14:15], v[10:11], 1, v[134:135]
	ds_read_b128 v[10:13], v145 offset:3456
	s_waitcnt lgkmcnt(1)
	global_store_dwordx4 v[14:15], v[6:9], off sc1
	s_nop 1
	v_or_b32_e32 v6, s4, v139
	v_mad_u64_u32 v[6:7], s[14:15], v6, s35, 0
	v_add_u32_e32 v7, s12, v7
	v_lshl_add_u64 v[6:7], v[6:7], 1, v[134:135]
	s_waitcnt lgkmcnt(0)
	global_store_dwordx4 v[6:7], v[10:13], off sc1
	ds_read_b128 v[6:9], v145 offset:4608
	s_nop 0
	v_or_b32_e32 v10, s4, v140
	v_mad_u64_u32 v[10:11], s[14:15], v10, s35, 0
	v_add_u32_e32 v11, s12, v11
	v_lshl_add_u64 v[14:15], v[10:11], 1, v[134:135]
	ds_read_b128 v[10:13], v145 offset:5760
	s_waitcnt lgkmcnt(1)
	global_store_dwordx4 v[14:15], v[6:9], off sc1
	s_nop 1
	v_or_b32_e32 v6, s4, v141
	v_mad_u64_u32 v[6:7], s[14:15], v6, s35, 0
	v_add_u32_e32 v7, s12, v7
	v_lshl_add_u64 v[6:7], v[6:7], 1, v[134:135]
	s_waitcnt lgkmcnt(0)
	global_store_dwordx4 v[6:7], v[10:13], off sc1
	ds_read_b128 v[6:9], v145 offset:6912
	s_nop 0
	v_or_b32_e32 v10, s4, v142
	v_mad_u64_u32 v[10:11], s[14:15], v10, s35, 0
	v_add_u32_e32 v11, s12, v11
	v_lshl_add_u64 v[14:15], v[10:11], 1, v[134:135]
	ds_read_b128 v[10:13], v145 offset:8064
	s_waitcnt lgkmcnt(1)
	global_store_dwordx4 v[14:15], v[6:9], off sc1
	s_nop 1
	v_or_b32_e32 v6, s4, v143
	v_mad_u64_u32 v[6:7], s[14:15], v6, s35, 0
	v_add_u32_e32 v7, s12, v7
	v_lshl_add_u64 v[6:7], v[6:7], 1, v[134:135]
	s_waitcnt lgkmcnt(0)
	global_store_dwordx4 v[6:7], v[10:13], off sc1
	s_waitcnt lgkmcnt(0)
	s_cbranch_scc0 .LBB0_47

; __device__ __forceinline__ unsigned cvt_pk_bf16(float lo, float hi) { unsigned r; asm("v_cvt_pk_bf16_f32 %0, %1, %2" : "=v"(r) : "v"(lo), "v"(hi)); return r; }
; __device__ __forceinline__ void p0_s5_group(const Args& a, LAS unsigned char* lds, int g, int tid) {
;     ...
;     for (int idx = tid; idx < 256 * 48; idx += NWAVES * 64) {
;         const int rr = idx / 48, cg = idx % 48, s = rr >> 4, c = rr & 15;
;         float v[8];
;         if (cg < 32) { const int sp = cg >> 1, c0 = (cg & 1) * 8;
; #pragma unroll
;             for (int i = 0; i < 8; ++i) { const int o = (((s - sp) & 15) * 16 + c) * 16 + c0 + i; v[i] = (sp <= s) ? Kt[o] + Kt2[o] : 0.f; }
;         } else { const int im = cg >= 40, p0 = (cg - (im ? 40 : 32)) * 8;
; #pragma unroll
;             for (int i = 0; i < 8; ++i) { const int p = p0 + i; const float cr = CRe[c * 64 + p], ci = CIm[c * 64 + p], lr = LPre[(s + 1) * 64 + p], li = LPim[(s + 1) * 64 + p];
;                 v[i] = im ? -(cr * li + ci * lr) : (cr * lr - ci * li); }
;         }
;         u32x4 o; o.x = cvt_pk_bf16(v[0], v[1]); o.y = cvt_pk_bf16(v[2], v[3]); o.z = cvt_pk_bf16(v[4], v[5]); o.w = cvt_pk_bf16(v[6], v[7]);
;         *(u32x4*)(MW + (size_t)rr * 384 + cg * 8) = o;
;     }
.LBB0_117:
	s_or_b64 exec, exec, s[4:5]
	v_mul_u32_u24_e32 v2, 0x180, v2
	v_lshlrev_b32_e32 v2, 1, v2
	s_movk_i32 s4, 0x2dff
	v_cvt_pk_bf16_f32 v62, v53, v48
	v_cvt_pk_bf16_f32 v63, v55, v54
	v_lshl_add_u64 v[54:55], s[16:17], 0, v[2:3]
	v_mov_b32_e32 v53, v3
	v_add_u32_e32 v2, 0x200, v39
	v_cmp_lt_u32_e32 vcc, s4, v39
	v_lshl_add_u64 v[52:53], v[52:53], 1, v[54:55]
	s_or_b64 s[96:97], vcc, s[96:97]
	v_mov_b32_e32 v39, v2
	v_cvt_pk_bf16_f32 v64, v58, v57
	v_cvt_pk_bf16_f32 v65, v59, v60
	global_store_dwordx4 v[52:53], v[62:65], off sc1
	s_andn2_b64 exec, exec, s[96:97]
	s_cbranch_execz .LBB0_137

; __device__ __forceinline__ unsigned cvt_pk_bf16(float lo, float hi) { unsigned r; asm("v_cvt_pk_bf16_f32 %0, %1, %2" : "=v"(r) : "v"(lo), "v"(hi)); return r; }
; __device__ __forceinline__ void p0_s5_group(const Args& a, LAS unsigned char* lds, int g, int tid) {
;     ...
;     for (int idx = tid; idx < 128 * 32; idx += NWAVES * 64) {
;         const int n = idx >> 5, cg = idx & 31, p = n & 63, im = n >> 6, sp = cg >> 1, c0 = (cg & 1) * 8;
;         const float lr = LPre[(15 - sp) * 64 + p], li = LPim[(15 - sp) * 64 + p];
;         float v[8];
; #pragma unroll
;         for (int i = 0; i < 8; ++i) { const float br = BBre[p * 16 + c0 + i], bi = BBim[p * 16 + c0 + i]; v[i] = im ? (lr * bi + li * br) : (lr * br - li * bi); }
;         u32x4 o; o.x = cvt_pk_bf16(v[0], v[1]); o.y = cvt_pk_bf16(v[2], v[3]); o.z = cvt_pk_bf16(v[4], v[5]); o.w = cvt_pk_bf16(v[6], v[7]);
;         *(u32x4*)(Win + (size_t)n * 256 + cg * 8) = o;
;     }
;     {
;         float* aux = (float*)(a.ws + WS_S5AUX) + (size_t)g * S5AUX_GROUP_FLOATS;
;         for (int idx = tid; idx < 64; idx += NWAVES * 64) { aux[idx] = LPre[64 + idx]; aux[64 + idx] = LPim[64 + idx]; aux[128 + idx] = LPre[16 * 64 + idx]; aux[192 + idx] = LPim[16 * 64 + idx]; }
;         for (int idx = tid; idx < 1024; idx += NWAVES * 64) { aux[256 + idx] = BBre[idx]; aux[1280 + idx] = BBim[idx]; }
;     }
.LBB0_138:
	v_and_b32_e32 v56, 8, v39
	v_and_b32_e32 v55, 63, v2
	s_movk_i32 s4, 0x3c0
	v_lshlrev_b32_e32 v56, 2, v56
	v_bitop3_b32 v57, v48, s4, v55 bitop3:0x26
	v_lshl_or_b32 v55, v55, 6, v56
	v_lshl_add_u32 v57, v57, 2, 0
	v_add_u32_e32 v55, 0, v55
	ds_read2st64_b32 v[88:89], v57 offset1:17
	ds_read_b128 v[56:59], v55 offset:8704
	ds_read_b128 v[60:63], v55 offset:8720
	ds_read_b128 v[64:67], v55 offset:12800
	s_movk_i32 s4, 0x800
	v_cmp_gt_u32_e32 vcc, s4, v54
	s_waitcnt lgkmcnt(2)
	v_mov_b32_e32 v92, v56
	v_mov_b32_e32 v90, v89
	v_mov_b32_e32 v91, v88
	s_waitcnt lgkmcnt(0)
	v_mov_b32_e32 v93, v64
	v_pk_mul_f32 v[94:95], v[90:91], v[92:93]
	v_pk_mul_f32 v[92:93], v[88:89], v[92:93]
	v_add_f32_e32 v56, v94, v95
	v_sub_f32_e32 v64, v92, v93
	v_cndmask_b32_e32 v87, v56, v64, vcc
	v_mov_b32_e32 v64, v57
	v_pk_mul_f32 v[56:57], v[90:91], v[64:65]
	s_mov_b64 s[4:5], 0x2000
	v_add_f32_e32 v92, v56, v57
	v_pk_mul_f32 v[56:57], v[88:89], v[64:65]
	v_add_u32_e32 v48, 0x4000, v48
	v_sub_f32_e32 v56, v56, v57
	v_cndmask_b32_e32 v92, v92, v56, vcc
	v_mov_b32_e32 v56, v58
	v_mov_b32_e32 v57, v66
	v_pk_mul_f32 v[64:65], v[90:91], v[56:57]
	v_pk_mul_f32 v[56:57], v[88:89], v[56:57]
	v_add_f32_e32 v58, v64, v65
	v_sub_f32_e32 v56, v56, v57
	v_mov_b32_e32 v66, v59
	v_cndmask_b32_e32 v93, v58, v56, vcc
	v_pk_mul_f32 v[56:57], v[90:91], v[66:67]
	v_mov_b32_e32 v64, v60
	v_add_f32_e32 v58, v56, v57
	v_pk_mul_f32 v[56:57], v[88:89], v[66:67]
	v_add_u32_e32 v39, 0x1000, v39
	v_sub_f32_e32 v56, v56, v57
	v_cndmask_b32_e32 v94, v58, v56, vcc
	ds_read_b128 v[56:59], v55 offset:12816
	v_add_u32_e32 v2, 16, v2
	s_waitcnt lgkmcnt(0)
	v_mov_b32_e32 v65, v56
	v_pk_mul_f32 v[66:67], v[90:91], v[64:65]
	v_pk_mul_f32 v[64:65], v[88:89], v[64:65]
	v_add_f32_e32 v55, v66, v67
	v_sub_f32_e32 v56, v64, v65
	v_cndmask_b32_e32 v55, v55, v56, vcc
	v_mov_b32_e32 v56, v61
	v_pk_mul_f32 v[60:61], v[90:91], v[56:57]
	v_pk_mul_f32 v[56:57], v[88:89], v[56:57]
	v_add_f32_e32 v60, v60, v61
	v_sub_f32_e32 v56, v56, v57
	v_cndmask_b32_e32 v64, v60, v56, vcc
	v_mov_b32_e32 v56, v62
	v_mov_b32_e32 v57, v58
	v_pk_mul_f32 v[60:61], v[90:91], v[56:57]
	v_pk_mul_f32 v[56:57], v[88:89], v[56:57]
	v_add_f32_e32 v58, v60, v61
	v_sub_f32_e32 v56, v56, v57
	v_cndmask_b32_e32 v60, v58, v56, vcc
	v_mov_b32_e32 v58, v63
	v_pk_mul_f32 v[56:57], v[90:91], v[58:59]
	s_nop 0
	v_add_f32_e32 v61, v56, v57
	v_pk_mul_f32 v[56:57], v[88:89], v[58:59]
	v_cvt_pk_bf16_f32 v58, v55, v64
	v_add_u32_e32 v55, 0x200, v54
	v_sub_f32_e32 v56, v56, v57
	v_cndmask_b32_e32 v59, v61, v56, vcc
	v_cvt_pk_bf16_f32 v56, v87, v92
	v_cvt_pk_bf16_f32 v57, v93, v94
	v_cvt_pk_bf16_f32 v59, v60, v59
	global_store_dwordx4 v[52:53], v[56:59], off sc1
	v_lshl_add_u64 v[52:53], v[52:53], 0, s[4:5]
	s_movk_i32 s4, 0xdff
	v_cmp_lt_u32_e32 vcc, s4, v54
	s_or_b64 s[16:17], vcc, s[16:17]
	v_mov_b32_e32 v54, v55
	s_andn2_b64 exec, exec, s[16:17]
	s_cbranch_execnz .LBB0_138
	s_or_b64 exec, exec, s[16:17]
	s_and_saveexec_b64 s[4:5], s[14:15]
	s_cbranch_execz .LBB0_141
	ds_read2st64_b32 v[52:53], v71 offset0:1 offset1:16
	ds_read2st64_b32 v[54:55], v71 offset0:18 offset1:33
	s_mul_i32 s16, s94, 0x2400
	s_mul_hi_i32 s17, s94, 0x2400
	s_add_u32 s16, s33, s16
	s_addc_u32 s17, s34, s17
	v_lshlrev_b32_e32 v2, 2, v0
	s_waitcnt lgkmcnt(1)
	global_store_dword v2, v52, s[16:17]
	s_waitcnt lgkmcnt(0)
	global_store_dword v2, v54, s[16:17] offset:256
	global_store_dword v2, v53, s[16:17] offset:512
	global_store_dword v2, v55, s[16:17] offset:768

; __device__ __forceinline__ void p0_task(const float* W, int N, const float* gk, bf16_t* WT, int ldt, int k0, int n0, int nd0, LAS unsigned char* stg, int lane) {
;     const float* src = W + (size_t)k0 * N + n0 + 2 * lane;
;     f32x2 v[64];
;     ...
;     { const float* p = src; const size_t step = (size_t)N;
; #pragma unroll
;       for (int i = 0; i < 64; ++i) { v[i] = __builtin_nontemporal_load((const f32x2*)p); p += step; if ((i & 7) == 7) asm volatile("" : "+v"(p)); } }
;     ...
; #pragma unroll
;     for (int i = 0; i < 64; ++i) v[i] = __builtin_nontemporal_load((const f32x2*)(src + (size_t)i * N));
;     ...
;         const int nkb = K / 64, nb = r / nkb, kb = r % nkb, k0 = kb * 64, n0 = nb * 128;
;         if (dual == 2) { gk = k0 < DH ? a.in[I_GS5] : a.in[I_GLRU] - DH; dual = 0; }
;         p0_task(W, N, gk, WT, K, k0, n0, dual ? (nb * 256 + off) : n0, stg, lane);
.LBB0_152:
	s_ashr_i32 s8, s4, 31
	s_lshr_b32 s8, s8, 28
	s_add_i32 s8, s4, s8
	s_ashr_i32 s8, s8, 4
	s_lshl_b32 s9, s8, 10
	s_sub_i32 s10, s5, s9
	s_ashr_i32 s11, s10, 31
	s_lshl_b32 s8, s8, 7
	s_lshl_b64 s[54:55], s[10:11], 12
	s_add_u32 s54, s56, s54
	s_addc_u32 s55, s57, s55
	s_ashr_i32 s9, s8, 31
	v_lshl_add_u64 v[22:23], s[10:11], 1, v[4:5]
	s_lshl_b64 s[10:11], s[8:9], 2
	s_add_u32 s10, s54, s10
	s_addc_u32 s11, s55, s11
	v_lshl_add_u64 v[34:35], s[10:11], 0, v[2:3]
	v_add_co_u32_e32 v52, vcc, s7, v34
	global_load_dwordx2 v[66:67], v2, s[10:11] nt
	s_nop 0
	v_addc_co_u32_e32 v53, vcc, 0, v35, vcc
	v_add_co_u32_e32 v54, vcc, s12, v34
	v_or_b32_e32 v6, s8, v24
	s_nop 0
	v_addc_co_u32_e32 v55, vcc, 0, v35, vcc
	v_add_co_u32_e32 v56, vcc, s13, v34
	v_or_b32_e32 v8, s8, v25
	s_nop 0
	v_addc_co_u32_e32 v57, vcc, 0, v35, vcc
	v_add_co_u32_e32 v58, vcc, s14, v34
	v_or_b32_e32 v10, s8, v26
	s_nop 0
	v_addc_co_u32_e32 v59, vcc, 0, v35, vcc
	v_add_co_u32_e32 v60, vcc, s15, v34
	v_or_b32_e32 v12, s8, v27
	s_nop 0
	v_addc_co_u32_e32 v61, vcc, 0, v35, vcc
	v_add_co_u32_e32 v62, vcc, s16, v34
	v_or_b32_e32 v14, s8, v28
	s_nop 0
	v_addc_co_u32_e32 v63, vcc, 0, v35, vcc
	v_add_co_u32_e32 v64, vcc, s17, v34
	v_or_b32_e32 v16, s8, v29
	s_nop 0
	v_addc_co_u32_e32 v65, vcc, 0, v35, vcc
	v_add_co_u32_e32 v68, vcc, s28, v34
	v_or_b32_e32 v18, s8, v30
	s_nop 0
	v_addc_co_u32_e32 v69, vcc, 0, v35, vcc
	v_add_co_u32_e32 v70, vcc, s29, v34
	v_or_b32_e32 v20, s8, v31
	s_nop 0
	v_addc_co_u32_e32 v71, vcc, 0, v35, vcc
	v_add_co_u32_e32 v72, vcc, s30, v34
	s_or_b32 s8, s8, 1
	s_nop 0
	v_addc_co_u32_e32 v73, vcc, 0, v35, vcc
	v_add_co_u32_e32 v74, vcc, s31, v34
	v_or_b32_e32 v36, s8, v24
	s_nop 0
	v_addc_co_u32_e32 v75, vcc, 0, v35, vcc
	v_add_co_u32_e32 v76, vcc, s33, v34
	v_or_b32_e32 v38, s8, v25
	s_nop 0
	v_addc_co_u32_e32 v77, vcc, 0, v35, vcc
	v_add_co_u32_e32 v78, vcc, s34, v34
	v_or_b32_e32 v40, s8, v26
	s_nop 0
	v_addc_co_u32_e32 v79, vcc, 0, v35, vcc
	v_add_co_u32_e32 v80, vcc, s35, v34
	v_or_b32_e32 v42, s8, v27
	s_nop 0
	v_addc_co_u32_e32 v81, vcc, 0, v35, vcc
	v_add_co_u32_e32 v82, vcc, s36, v34
	v_or_b32_e32 v44, s8, v28
	s_nop 0
	v_addc_co_u32_e32 v83, vcc, 0, v35, vcc
	v_add_co_u32_e32 v84, vcc, s37, v34
	v_or_b32_e32 v46, s8, v29
	s_nop 0
	v_addc_co_u32_e32 v85, vcc, 0, v35, vcc
	v_add_co_u32_e32 v86, vcc, s38, v34
	v_or_b32_e32 v48, s8, v30
	s_nop 0
	v_addc_co_u32_e32 v87, vcc, 0, v35, vcc
	v_add_co_u32_e32 v88, vcc, s39, v34
	v_or_b32_e32 v50, s8, v31
	s_nop 0
	v_addc_co_u32_e32 v89, vcc, 0, v35, vcc
	v_add_co_u32_e32 v90, vcc, s40, v34
	v_ashrrev_i32_e32 v37, 31, v36
	s_nop 0
	v_addc_co_u32_e32 v91, vcc, 0, v35, vcc
	v_add_co_u32_e32 v92, vcc, s41, v34
	v_ashrrev_i32_e32 v39, 31, v38
	s_nop 0
	v_addc_co_u32_e32 v93, vcc, 0, v35, vcc
	v_add_co_u32_e32 v94, vcc, s42, v34
	v_ashrrev_i32_e32 v7, 31, v6
	s_nop 0
	v_addc_co_u32_e32 v95, vcc, 0, v35, vcc
	v_add_co_u32_e32 v96, vcc, s43, v34
	v_ashrrev_i32_e32 v9, 31, v8
	s_nop 0
	v_addc_co_u32_e32 v97, vcc, 0, v35, vcc
	v_add_co_u32_e32 v98, vcc, s44, v34
	v_ashrrev_i32_e32 v11, 31, v10
	s_nop 0
	v_addc_co_u32_e32 v99, vcc, 0, v35, vcc
	v_add_co_u32_e32 v100, vcc, s45, v34
	v_ashrrev_i32_e32 v13, 31, v12
	s_nop 0
	v_addc_co_u32_e32 v101, vcc, 0, v35, vcc
	v_add_co_u32_e32 v102, vcc, s46, v34
	v_ashrrev_i32_e32 v15, 31, v14
	s_nop 0
	v_addc_co_u32_e32 v103, vcc, 0, v35, vcc
	v_add_co_u32_e32 v104, vcc, s47, v34
	v_ashrrev_i32_e32 v17, 31, v16
	s_nop 0
	v_addc_co_u32_e32 v105, vcc, 0, v35, vcc
	v_add_co_u32_e32 v106, vcc, s48, v34
	v_ashrrev_i32_e32 v19, 31, v18
	s_nop 0
	v_addc_co_u32_e32 v107, vcc, 0, v35, vcc
	v_add_co_u32_e32 v108, vcc, s49, v34
	v_ashrrev_i32_e32 v21, 31, v20
	s_nop 0
	v_addc_co_u32_e32 v109, vcc, 0, v35, vcc
	v_add_co_u32_e32 v110, vcc, s50, v34
	v_ashrrev_i32_e32 v41, 31, v40
	s_nop 0
	v_addc_co_u32_e32 v111, vcc, 0, v35, vcc
	v_add_co_u32_e32 v112, vcc, s51, v34
	v_ashrrev_i32_e32 v43, 31, v42
	s_nop 0
	v_addc_co_u32_e32 v113, vcc, 0, v35, vcc
	v_add_co_u32_e32 v114, vcc, s52, v34
	v_ashrrev_i32_e32 v45, 31, v44
	s_nop 0
	v_addc_co_u32_e32 v115, vcc, 0, v35, vcc
	v_add_co_u32_e32 v34, vcc, s53, v34
	v_ashrrev_i32_e32 v47, 31, v46
	s_nop 0
	v_addc_co_u32_e32 v35, vcc, 0, v35, vcc
	global_load_dwordx2 v[116:117], v[52:53], off offset:-4096 nt
	global_load_dwordx2 v[118:119], v[52:53], off nt
	global_load_dwordx2 v[120:121], v[54:55], off offset:-4096 nt
	global_load_dwordx2 v[122:123], v[54:55], off nt
	global_load_dwordx2 v[124:125], v[56:57], off offset:-4096 nt
	global_load_dwordx2 v[126:127], v[56:57], off nt
	global_load_dwordx2 v[128:129], v[58:59], off offset:-4096 nt
	global_load_dwordx2 v[130:131], v[58:59], off nt
	global_load_dwordx2 v[132:133], v[60:61], off offset:-4096 nt
	global_load_dwordx2 v[134:135], v[60:61], off nt
	global_load_dwordx2 v[136:137], v[62:63], off offset:-4096 nt
	global_load_dwordx2 v[138:139], v[62:63], off nt
	global_load_dwordx2 v[140:141], v[64:65], off offset:-4096 nt
	global_load_dwordx2 v[142:143], v[64:65], off nt
	global_load_dwordx2 v[144:145], v[68:69], off offset:-4096 nt
	global_load_dwordx2 v[146:147], v[68:69], off nt
	global_load_dwordx2 v[148:149], v[70:71], off offset:-4096 nt
	global_load_dwordx2 v[150:151], v[70:71], off nt
	global_load_dwordx2 v[152:153], v[72:73], off offset:-4096 nt
	global_load_dwordx2 v[154:155], v[72:73], off nt
	global_load_dwordx2 v[156:157], v[74:75], off offset:-4096 nt
	global_load_dwordx2 v[158:159], v[74:75], off nt
	global_load_dwordx2 v[160:161], v[76:77], off offset:-4096 nt
	global_load_dwordx2 v[162:163], v[76:77], off nt
	global_load_dwordx2 v[164:165], v[78:79], off offset:-4096 nt
; __device__ __forceinline__ unsigned cvt_pk_bf16(float lo, float hi) { unsigned r; asm("v_cvt_pk_bf16_f32 %0, %1, %2" : "=v"(r) : "v"(lo), "v"(hi)); return r; }
; __device__ __forceinline__ void p0_task(const float* W, int N, const float* gk, bf16_t* WT, int ldt, int k0, int n0, int nd0, LAS unsigned char* stg, int lane) {
;     ...
;     for (int i = 0; i < 64; ++i) v[i] = __builtin_nontemporal_load((const f32x2*)(src + (size_t)i * N));
;     ...
;     if (gk) {
; #pragma unroll
;         for (int i = 0; i < 64; ++i) v[i] = v[i] * gk[k0 + i];
;     }
; #pragma unroll
;     for (int j = 0; j < 2; ++j) {
; #pragma unroll
;         for (int kb = 0; kb < 8; ++kb) {
;             u32x4 o; o.x = cvt_pk_bf16(v[8 * kb][j], v[8 * kb + 1][j]); o.y = cvt_pk_bf16(v[8 * kb + 2][j], v[8 * kb + 3][j]); o.z = cvt_pk_bf16(v[8 * kb + 4][j], v[8 * kb + 5][j]); o.w = cvt_pk_bf16(v[8 * kb + 6][j], v[8 * kb + 7][j]);
	s_nop 0
	global_load_dwordx2 v[78:79], v[78:79], off nt
	s_nop 0
	global_load_dwordx2 v[166:167], v[80:81], off offset:-4096 nt
	s_nop 0
	global_load_dwordx2 v[80:81], v[80:81], off nt
	s_nop 0
	global_load_dwordx2 v[168:169], v[82:83], off offset:-4096 nt
	s_nop 0
	global_load_dwordx2 v[82:83], v[82:83], off nt
	s_nop 0
	global_load_dwordx2 v[170:171], v[84:85], off offset:-4096 nt
	s_nop 0
	global_load_dwordx2 v[84:85], v[84:85], off nt
	s_nop 0
	global_load_dwordx2 v[172:173], v[86:87], off offset:-4096 nt
	s_nop 0
	global_load_dwordx2 v[86:87], v[86:87], off nt
	s_nop 0
	global_load_dwordx2 v[174:175], v[88:89], off offset:-4096 nt
	s_nop 0
	global_load_dwordx2 v[88:89], v[88:89], off nt
	s_nop 0
	global_load_dwordx2 v[176:177], v[90:91], off offset:-4096 nt
	s_nop 0
	global_load_dwordx2 v[90:91], v[90:91], off nt
	s_nop 0
	global_load_dwordx2 v[178:179], v[92:93], off offset:-4096 nt
	s_nop 0
	global_load_dwordx2 v[92:93], v[92:93], off nt
	s_nop 0
	global_load_dwordx2 v[180:181], v[94:95], off offset:-4096 nt
	s_nop 0
	global_load_dwordx2 v[94:95], v[94:95], off nt
	s_nop 0
	global_load_dwordx2 v[184:185], v[96:97], off offset:-4096 nt
	s_nop 0
	global_load_dwordx2 v[96:97], v[96:97], off nt
	s_nop 0
	global_load_dwordx2 v[186:187], v[98:99], off offset:-4096 nt
	s_nop 0
	global_load_dwordx2 v[98:99], v[98:99], off nt
	s_nop 0
	global_load_dwordx2 v[188:189], v[100:101], off offset:-4096 nt
	s_nop 0
	global_load_dwordx2 v[100:101], v[100:101], off nt
	s_nop 0
	global_load_dwordx2 v[190:191], v[102:103], off offset:-4096 nt
	s_nop 0
	global_load_dwordx2 v[102:103], v[102:103], off nt
	s_nop 0
	global_load_dwordx2 v[192:193], v[104:105], off offset:-4096 nt
	s_nop 0
	global_load_dwordx2 v[104:105], v[104:105], off nt
	s_nop 0
	global_load_dwordx2 v[194:195], v[106:107], off offset:-4096 nt
	s_nop 0
	global_load_dwordx2 v[106:107], v[106:107], off nt
	s_nop 0
	global_load_dwordx2 v[196:197], v[108:109], off offset:-4096 nt
	s_nop 0
	global_load_dwordx2 v[108:109], v[108:109], off nt
	s_nop 0
	global_load_dwordx2 v[198:199], v[110:111], off offset:-4096 nt
	s_nop 0
	global_load_dwordx2 v[110:111], v[110:111], off nt
	s_nop 0
	global_load_dwordx2 v[200:201], v[112:113], off offset:-4096 nt
	s_nop 0
	global_load_dwordx2 v[112:113], v[112:113], off nt
	s_nop 0
	global_load_dwordx2 v[202:203], v[114:115], off offset:-4096 nt
	s_nop 0
	global_load_dwordx2 v[114:115], v[114:115], off nt
	s_nop 0
	global_load_dwordx2 v[204:205], v[34:35], off nt
	v_ashrrev_i32_e32 v49, 31, v48
	v_ashrrev_i32_e32 v51, 31, v50
	v_lshlrev_b64 v[34:35], 11, v[36:37]
	v_lshlrev_b64 v[36:37], 11, v[38:39]
	v_lshlrev_b64 v[6:7], 11, v[6:7]
	v_lshlrev_b64 v[8:9], 11, v[8:9]
	v_lshlrev_b64 v[10:11], 11, v[10:11]
	v_lshlrev_b64 v[12:13], 11, v[12:13]
	v_lshlrev_b64 v[14:15], 11, v[14:15]
	v_lshlrev_b64 v[16:17], 11, v[16:17]
	v_lshlrev_b64 v[18:19], 11, v[18:19]
	v_lshlrev_b64 v[20:21], 11, v[20:21]
	v_lshlrev_b64 v[38:39], 11, v[40:41]
	v_lshlrev_b64 v[40:41], 11, v[42:43]
	v_lshlrev_b64 v[42:43], 11, v[44:45]
	v_lshlrev_b64 v[44:45], 11, v[46:47]
	v_lshlrev_b64 v[46:47], 11, v[48:49]
	v_lshlrev_b64 v[48:49], 11, v[50:51]
	v_lshl_add_u64 v[206:207], v[22:23], 0, v[34:35]
	v_lshl_add_u64 v[208:209], v[22:23], 0, v[36:37]
	s_waitcnt vmcnt(62)
	v_cvt_pk_bf16_f32 v34, v66, v116
	s_waitcnt vmcnt(60)
	v_cvt_pk_bf16_f32 v35, v118, v120
	s_waitcnt vmcnt(58)
	v_cvt_pk_bf16_f32 v36, v122, v124
	s_waitcnt vmcnt(56)
	v_cvt_pk_bf16_f32 v37, v126, v128
	v_lshl_add_u64 v[6:7], v[22:23], 0, v[6:7]
	v_lshl_add_u64 v[8:9], v[22:23], 0, v[8:9]
	v_lshl_add_u64 v[10:11], v[22:23], 0, v[10:11]
	v_lshl_add_u64 v[12:13], v[22:23], 0, v[12:13]
	v_lshl_add_u64 v[14:15], v[22:23], 0, v[14:15]
	v_lshl_add_u64 v[16:17], v[22:23], 0, v[16:17]
	v_lshl_add_u64 v[18:19], v[22:23], 0, v[18:19]
	v_lshl_add_u64 v[20:21], v[22:23], 0, v[20:21]
	v_lshl_add_u64 v[212:213], v[22:23], 0, v[38:39]
	v_lshl_add_u64 v[214:215], v[22:23], 0, v[40:41]
	v_lshl_add_u64 v[216:217], v[22:23], 0, v[42:43]
	v_lshl_add_u64 v[218:219], v[22:23], 0, v[44:45]
	v_lshl_add_u64 v[220:221], v[22:23], 0, v[46:47]
	v_lshl_add_u64 v[22:23], v[22:23], 0, v[48:49]
	s_waitcnt vmcnt(54)
	v_cvt_pk_bf16_f32 v38, v130, v132
	s_waitcnt vmcnt(52)
	v_cvt_pk_bf16_f32 v39, v134, v136
	s_waitcnt vmcnt(50)
	v_cvt_pk_bf16_f32 v40, v138, v140
	s_waitcnt vmcnt(48)
	v_cvt_pk_bf16_f32 v41, v142, v144
	s_waitcnt vmcnt(46)
	v_cvt_pk_bf16_f32 v42, v146, v148
	s_waitcnt vmcnt(44)
	v_cvt_pk_bf16_f32 v43, v150, v152
	s_waitcnt vmcnt(42)
	v_cvt_pk_bf16_f32 v44, v154, v156
	s_waitcnt vmcnt(40)
	v_cvt_pk_bf16_f32 v45, v158, v160
	s_waitcnt vmcnt(38)
	v_cvt_pk_bf16_f32 v46, v162, v164
	s_waitcnt vmcnt(36)
; #define LAS __attribute__((address_space(3)))
; __device__ __forceinline__ unsigned cvt_pk_bf16(float lo, float hi) { unsigned r; asm("v_cvt_pk_bf16_f32 %0, %1, %2" : "=v"(r) : "v"(lo), "v"(hi)); return r; }
; #define LDS_WAIT() asm volatile("s_waitcnt lgkmcnt(0)" ::: "memory")
; __device__ __forceinline__ void p0_task(const float* W, int N, const float* gk, bf16_t* WT, int ldt, int k0, int n0, int nd0, LAS unsigned char* stg, int lane) {
;     ...
; #pragma unroll
;     for (int j = 0; j < 2; ++j) {
; #pragma unroll
;         for (int kb = 0; kb < 8; ++kb) {
;             u32x4 o; o.x = cvt_pk_bf16(v[8 * kb][j], v[8 * kb + 1][j]); o.y = cvt_pk_bf16(v[8 * kb + 2][j], v[8 * kb + 3][j]); o.z = cvt_pk_bf16(v[8 * kb + 4][j], v[8 * kb + 5][j]); o.w = cvt_pk_bf16(v[8 * kb + 6][j], v[8 * kb + 7][j]);
;             *(LAS u32x4*)(stg + lane * STG_PITCH + kb * 16) = o;
;         }
;         LDS_WAIT(); asm volatile("" ::: "memory");
; #pragma unroll
;         for (int it = 0; it < 8; ++it) {
;             const int rr = 8 * it + (lane >> 3), kb = lane & 7;
;             const u32x4 o = *(const LAS u32x4*)(stg + rr * STG_PITCH + kb * 16);
;             *(u32x4*)(WT + (size_t)(nd0 + 2 * rr + j) * ldt + k0 + 8 * kb) = o;
;         }
;         LDS_WAIT(); asm volatile("" ::: "memory");
;     }
	v_cvt_pk_bf16_f32 v47, v78, v166
	s_waitcnt vmcnt(34)
	v_cvt_pk_bf16_f32 v48, v80, v168
	s_waitcnt vmcnt(32)
	v_cvt_pk_bf16_f32 v49, v82, v170
	s_waitcnt vmcnt(30)
	v_cvt_pk_bf16_f32 v50, v84, v172
	s_waitcnt vmcnt(28)
	v_cvt_pk_bf16_f32 v51, v86, v174
	s_waitcnt vmcnt(26)
	v_cvt_pk_bf16_f32 v52, v88, v176
	s_waitcnt vmcnt(24)
	v_cvt_pk_bf16_f32 v53, v90, v178
	s_waitcnt vmcnt(22)
	v_cvt_pk_bf16_f32 v54, v92, v180
	s_waitcnt vmcnt(20)
	v_cvt_pk_bf16_f32 v55, v94, v184
	s_waitcnt vmcnt(18)
	v_cvt_pk_bf16_f32 v56, v96, v186
	s_waitcnt vmcnt(16)
	v_cvt_pk_bf16_f32 v57, v98, v188
	s_waitcnt vmcnt(14)
	v_cvt_pk_bf16_f32 v58, v100, v190
	s_waitcnt vmcnt(12)
	v_cvt_pk_bf16_f32 v59, v102, v192
	s_waitcnt vmcnt(10)
	v_cvt_pk_bf16_f32 v60, v104, v194
	s_waitcnt vmcnt(8)
	v_cvt_pk_bf16_f32 v61, v106, v196
	s_waitcnt vmcnt(6)
	v_cvt_pk_bf16_f32 v62, v108, v198
	s_waitcnt vmcnt(4)
	v_cvt_pk_bf16_f32 v63, v110, v200
	s_waitcnt vmcnt(2)
	v_cvt_pk_bf16_f32 v64, v112, v202
	s_waitcnt vmcnt(0)
	v_cvt_pk_bf16_f32 v65, v114, v204
	ds_write_b128 v32, v[34:37]
	ds_write_b128 v32, v[38:41] offset:16
	ds_write_b128 v32, v[42:45] offset:32
	ds_write_b128 v32, v[46:49] offset:48
	ds_write_b128 v32, v[50:53] offset:64
	ds_write_b128 v32, v[54:57] offset:80
	ds_write_b128 v32, v[58:61] offset:96
	ds_write_b128 v32, v[62:65] offset:112
	s_waitcnt lgkmcnt(0)
	ds_read_b128 v[34:37], v33
	ds_read_b128 v[38:41], v33 offset:1152
	ds_read_b128 v[42:45], v33 offset:2304
	ds_read_b128 v[46:49], v33 offset:3456
	ds_read_b128 v[50:53], v33 offset:4608
	ds_read_b128 v[54:57], v33 offset:5760
	ds_read_b128 v[58:61], v33 offset:6912
	ds_read_b128 v[62:65], v33 offset:8064
	s_waitcnt lgkmcnt(7)
	global_store_dwordx4 v[6:7], v[34:37], off sc1
	s_waitcnt lgkmcnt(6)
	global_store_dwordx4 v[8:9], v[38:41], off sc1
	s_waitcnt lgkmcnt(5)
	global_store_dwordx4 v[10:11], v[42:45], off sc1
	s_waitcnt lgkmcnt(4)
	global_store_dwordx4 v[12:13], v[46:49], off sc1
	s_waitcnt lgkmcnt(3)
	global_store_dwordx4 v[14:15], v[50:53], off sc1
	s_waitcnt lgkmcnt(2)
	global_store_dwordx4 v[16:17], v[54:57], off sc1
	s_waitcnt lgkmcnt(1)
	global_store_dwordx4 v[18:19], v[58:61], off sc1
	s_waitcnt lgkmcnt(0)
	global_store_dwordx4 v[20:21], v[62:65], off sc1
	v_cvt_pk_bf16_f32 v66, v67, v117
	v_cvt_pk_bf16_f32 v67, v119, v121
	v_cvt_pk_bf16_f32 v68, v123, v125
	v_cvt_pk_bf16_f32 v69, v127, v129
	s_waitcnt lgkmcnt(0)
	v_cvt_pk_bf16_f32 v70, v131, v133
	v_cvt_pk_bf16_f32 v71, v135, v137
	v_cvt_pk_bf16_f32 v72, v139, v141
	v_cvt_pk_bf16_f32 v73, v143, v145
	v_cvt_pk_bf16_f32 v74, v147, v149
	v_cvt_pk_bf16_f32 v75, v151, v153
	v_cvt_pk_bf16_f32 v76, v155, v157
	v_cvt_pk_bf16_f32 v77, v159, v161
	v_cvt_pk_bf16_f32 v78, v163, v165
	v_cvt_pk_bf16_f32 v79, v79, v167
	v_cvt_pk_bf16_f32 v80, v81, v169
	v_cvt_pk_bf16_f32 v81, v83, v171
	v_cvt_pk_bf16_f32 v82, v85, v173
	v_cvt_pk_bf16_f32 v83, v87, v175
	v_cvt_pk_bf16_f32 v84, v89, v177
	v_cvt_pk_bf16_f32 v85, v91, v179
	v_cvt_pk_bf16_f32 v86, v93, v181
	v_cvt_pk_bf16_f32 v87, v95, v185
	v_cvt_pk_bf16_f32 v88, v97, v187
	v_cvt_pk_bf16_f32 v89, v99, v189
	v_cvt_pk_bf16_f32 v90, v101, v191
	v_cvt_pk_bf16_f32 v91, v103, v193
	v_cvt_pk_bf16_f32 v92, v105, v195
	v_cvt_pk_bf16_f32 v93, v107, v197
	v_cvt_pk_bf16_f32 v94, v109, v199
	v_cvt_pk_bf16_f32 v95, v111, v201
	v_cvt_pk_bf16_f32 v96, v113, v203
	v_cvt_pk_bf16_f32 v97, v115, v205
	ds_write_b128 v32, v[66:69]
	ds_write_b128 v32, v[70:73] offset:16
	ds_write_b128 v32, v[74:77] offset:32
	ds_write_b128 v32, v[78:81] offset:48
	ds_write_b128 v32, v[82:85] offset:64
	ds_write_b128 v32, v[86:89] offset:80
	ds_write_b128 v32, v[90:93] offset:96
	ds_write_b128 v32, v[94:97] offset:112
	s_waitcnt lgkmcnt(0)
	ds_read_b128 v[6:9], v33
	ds_read_b128 v[10:13], v33 offset:1152
	ds_read_b128 v[14:17], v33 offset:2304
	ds_read_b128 v[18:21], v33 offset:3456
	ds_read_b128 v[34:37], v33 offset:4608
	ds_read_b128 v[38:41], v33 offset:5760
	ds_read_b128 v[42:45], v33 offset:6912
	ds_read_b128 v[46:49], v33 offset:8064
	s_waitcnt lgkmcnt(7)
	global_store_dwordx4 v[206:207], v[6:9], off sc1
	s_waitcnt lgkmcnt(6)
	global_store_dwordx4 v[208:209], v[10:13], off sc1
	s_waitcnt lgkmcnt(5)
	global_store_dwordx4 v[212:213], v[14:17], off sc1
	s_waitcnt lgkmcnt(4)
	global_store_dwordx4 v[214:215], v[18:21], off sc1
	s_waitcnt lgkmcnt(3)
	global_store_dwordx4 v[216:217], v[34:37], off sc1
	s_waitcnt lgkmcnt(2)
	global_store_dwordx4 v[218:219], v[38:41], off sc1
	s_waitcnt lgkmcnt(1)
	global_store_dwordx4 v[220:221], v[42:45], off sc1
	s_waitcnt lgkmcnt(0)
	global_store_dwordx4 v[22:23], v[46:49], off sc1
	s_waitcnt lgkmcnt(0)
	s_add_i32 s4, s4, 1
	s_add_i32 s5, s5, 64
	s_cmp_ge_i32 s4, s6
	s_cbranch_scc0 .LBB0_152

; __device__ __forceinline__ float fsilu(float x) { return x * fsigmoid(x); }
; __device__ __forceinline__ u32x4 pack8(const f32x4 a, const f32x4 b) { u32x4 w; w.x = cvt_pk_bf16(a[0], a[1]); w.y = cvt_pk_bf16(a[2], a[3]); w.z = cvt_pk_bf16(b[0], b[1]); w.w = cvt_pk_bf16(b[2], b[3]); return w; }
;     __device__ __forceinline__ void operator()(const Acc& acc, const Unit& u, int wr, int wc, int fr, int fq) const {
;         int row0 = u.pm * BM + wr * 64 + fr, colh = u.pn * 128 + wc * 32 + 8 * fq; asm volatile("" : "+v"(row0), "+v"(colh));
;         float sq[2][4];
; #pragma unroll
;         for (int ai = 0; ai < 2; ++ai)
; #pragma unroll
;             for (int m = 0; m < 4; ++m) sq[ai][m] = ssq[row0 + ai * HALF + m * 16];
;         asm volatile("" ::: "memory");
; #pragma unroll
;         for (int ai = 0; ai < 2; ++ai)
; #pragma unroll
;             for (int m = 0; m < 4; ++m) {
;                 const int row = row0 + ai * HALF + m * 16;
;                 const float r = rsqrtf(sq[ai][m] * (1.0f / D) + EPS);
;                 f32x4 h0, h1;
; #pragma unroll
;                 for (int j = 0; j < 4; ++j) { h0[j] = fsilu(acc[ai][0][m][0][j] * r) * (acc[ai][1][m][0][j] * r); h1[j] = fsilu(acc[ai][0][m][1][j] * r) * (acc[ai][1][m][1][j] * r); }
;                 *(u32x4*)(O + (size_t)row * FF + colh) = pack8(h0, h1);
;             }
.LBB0_172:
	v_lshl_add_u32 v144, s6, 8, v136
	v_lshl_or_b32 v145, s7, 7, v137
	v_lshlrev_b32_e32 v146, 2, v144
	global_load_dword v149, v146, s[88:89]
	global_load_dword v150, v146, s[88:89] offset:64
	global_load_dword v151, v146, s[88:89] offset:128
	global_load_dword v152, v146, s[88:89] offset:192
	global_load_dword v153, v146, s[88:89] offset:512
	global_load_dword v154, v146, s[88:89] offset:576
	global_load_dword v155, v146, s[88:89] offset:640
	global_load_dword v156, v146, s[88:89] offset:704
	v_readlane_b32 s6, v254, 40
	v_readlane_b32 s7, v254, 41
	v_mul_u32_u24_e32 v147, 0x2c00, v144
	v_lshl_add_u32 v147, v145, 1, v147
	v_pk_mul_f32 v[126:127], v[122:123], v[126:127]
	v_pk_mul_f32 v[128:129], v[124:125], v[128:129]
	v_pk_mul_f32 v[118:119], v[114:115], v[118:119]
	v_pk_mul_f32 v[120:121], v[116:117], v[120:121]
	v_pk_mul_f32 v[94:95], v[110:111], v[94:95]
	v_pk_mul_f32 v[96:97], v[112:113], v[96:97]
	v_pk_mul_f32 v[90:91], v[106:107], v[90:91]
	v_pk_mul_f32 v[92:93], v[108:109], v[92:93]
	v_pk_mul_f32 v[54:55], v[78:79], v[54:55]
	v_pk_mul_f32 v[56:57], v[80:81], v[56:57]
	v_pk_mul_f32 v[50:51], v[66:67], v[50:51]
	v_pk_mul_f32 v[52:53], v[68:69], v[52:53]
	v_pk_mul_f32 v[22:23], v[38:39], v[22:23]
	v_pk_mul_f32 v[24:25], v[40:41], v[24:25]
	v_pk_mul_f32 v[18:19], v[26:27], v[18:19]
	v_pk_mul_f32 v[20:21], v[28:29], v[20:21]
	v_pk_mul_f32 v[102:103], v[86:87], v[102:103]
	v_pk_mul_f32 v[104:105], v[88:89], v[104:105]
	v_pk_mul_f32 v[98:99], v[82:83], v[98:99]
	v_pk_mul_f32 v[100:101], v[84:85], v[100:101]
	v_pk_mul_f32 v[74:75], v[62:63], v[74:75]
	v_pk_mul_f32 v[76:77], v[64:65], v[76:77]
	v_pk_mul_f32 v[70:71], v[58:59], v[70:71]
	v_pk_mul_f32 v[72:73], v[60:61], v[72:73]
	v_pk_mul_f32 v[46:47], v[34:35], v[46:47]
	v_pk_mul_f32 v[48:49], v[36:37], v[48:49]
	v_pk_mul_f32 v[42:43], v[30:31], v[42:43]
	v_pk_mul_f32 v[44:45], v[32:33], v[44:45]
	v_pk_mul_f32 v[14:15], v[6:7], v[14:15]
	v_pk_mul_f32 v[16:17], v[8:9], v[16:17]
	v_pk_mul_f32 v[10:11], v[2:3], v[10:11]
	v_pk_mul_f32 v[12:13], v[4:5], v[12:13]
	s_waitcnt vmcnt(0)
	v_fmamk_f32 v158, v149, 0x3a000000, v143
	v_fmamk_f32 v160, v150, 0x3a000000, v143
	v_fmamk_f32 v162, v151, 0x3a000000, v143
	v_fmamk_f32 v164, v152, 0x3a000000, v143
	v_fmamk_f32 v166, v153, 0x3a000000, v143
	v_fmamk_f32 v168, v154, 0x3a000000, v143
	v_fmamk_f32 v170, v155, 0x3a000000, v143
	v_fmamk_f32 v172, v156, 0x3a000000, v143
	v_rsq_f32_e32 v174, v158
	v_rsq_f32_e32 v176, v160
	v_rsq_f32_e32 v178, v162
	v_rsq_f32_e32 v184, v164
	v_rsq_f32_e32 v186, v166
	v_rsq_f32_e32 v188, v168
	v_rsq_f32_e32 v190, v170
	v_rsq_f32_e32 v192, v172
	v_mul_f32_e32 v174, 0xbfb8aa3b, v174
	v_mul_f32_e32 v176, 0xbfb8aa3b, v176
	v_mul_f32_e32 v178, 0xbfb8aa3b, v178
	v_mul_f32_e32 v184, 0xbfb8aa3b, v184
	v_mul_f32_e32 v186, 0xbfb8aa3b, v186
	v_mul_f32_e32 v188, 0xbfb8aa3b, v188
	v_mul_f32_e32 v190, 0xbfb8aa3b, v190
	v_mul_f32_e32 v192, 0xbfb8aa3b, v192
	v_pk_mul_f32 v[194:195], v[122:123], v[174:175] op_sel_hi:[1,0]
	v_pk_mul_f32 v[196:197], v[124:125], v[174:175] op_sel_hi:[1,0]
	v_pk_mul_f32 v[198:199], v[114:115], v[174:175] op_sel_hi:[1,0]
	v_pk_mul_f32 v[200:201], v[116:117], v[174:175] op_sel_hi:[1,0]
	v_exp_f32_e32 v194, v194
	v_exp_f32_e32 v195, v195
	v_exp_f32_e32 v196, v196
	v_exp_f32_e32 v197, v197
	v_exp_f32_e32 v198, v198
	v_exp_f32_e32 v199, v199
	v_exp_f32_e32 v200, v200
	v_exp_f32_e32 v201, v201
	v_pk_fma_f32 v[194:195], v[194:195], v[158:159], v[158:159] op_sel_hi:[1,0,0]
	v_pk_fma_f32 v[196:197], v[196:197], v[158:159], v[158:159] op_sel_hi:[1,0,0]
	v_pk_fma_f32 v[198:199], v[198:199], v[158:159], v[158:159] op_sel_hi:[1,0,0]
	v_pk_fma_f32 v[200:201], v[200:201], v[158:159], v[158:159] op_sel_hi:[1,0,0]
	v_rcp_f32_e32 v194, v194
	v_rcp_f32_e32 v195, v195
	v_rcp_f32_e32 v196, v196
	v_rcp_f32_e32 v197, v197
	v_rcp_f32_e32 v198, v198
	v_rcp_f32_e32 v199, v199
	v_rcp_f32_e32 v200, v200
	v_rcp_f32_e32 v201, v201
	v_pk_mul_f32 v[126:127], v[126:127], v[194:195]
	v_pk_mul_f32 v[128:129], v[128:129], v[196:197]
	v_pk_mul_f32 v[118:119], v[118:119], v[198:199]
	v_pk_mul_f32 v[120:121], v[120:121], v[200:201]
	v_cvt_pk_bf16_f32 v122, v126, v127
	v_cvt_pk_bf16_f32 v123, v128, v129
	v_cvt_pk_bf16_f32 v124, v118, v119
	v_cvt_pk_bf16_f32 v125, v120, v121
	global_store_dwordx4 v147, v[122:125], s[6:7] sc1
	v_pk_mul_f32 v[194:195], v[110:111], v[176:177] op_sel_hi:[1,0]
	v_pk_mul_f32 v[196:197], v[112:113], v[176:177] op_sel_hi:[1,0]
	v_pk_mul_f32 v[198:199], v[106:107], v[176:177] op_sel_hi:[1,0]
	v_pk_mul_f32 v[200:201], v[108:109], v[176:177] op_sel_hi:[1,0]
	v_exp_f32_e32 v194, v194
	v_exp_f32_e32 v195, v195
	v_exp_f32_e32 v196, v196
	v_exp_f32_e32 v197, v197
	v_exp_f32_e32 v198, v198
	v_exp_f32_e32 v199, v199
	v_exp_f32_e32 v200, v200
	v_exp_f32_e32 v201, v201
	v_pk_fma_f32 v[194:195], v[194:195], v[160:161], v[160:161] op_sel_hi:[1,0,0]
	v_pk_fma_f32 v[196:197], v[196:197], v[160:161], v[160:161] op_sel_hi:[1,0,0]
	v_pk_fma_f32 v[198:199], v[198:199], v[160:161], v[160:161] op_sel_hi:[1,0,0]
	v_pk_fma_f32 v[200:201], v[200:201], v[160:161], v[160:161] op_sel_hi:[1,0,0]
	v_rcp_f32_e32 v194, v194
	v_rcp_f32_e32 v195, v195
	v_rcp_f32_e32 v196, v196
	v_rcp_f32_e32 v197, v197
	v_rcp_f32_e32 v198, v198
	v_rcp_f32_e32 v199, v199
	v_rcp_f32_e32 v200, v200
	v_rcp_f32_e32 v201, v201
	v_pk_mul_f32 v[94:95], v[94:95], v[194:195]
	v_pk_mul_f32 v[96:97], v[96:97], v[196:197]
	v_pk_mul_f32 v[90:91], v[90:91], v[198:199]
	v_pk_mul_f32 v[92:93], v[92:93], v[200:201]
	v_cvt_pk_bf16_f32 v110, v94, v95
	v_cvt_pk_bf16_f32 v111, v96, v97
	v_cvt_pk_bf16_f32 v112, v90, v91
	v_cvt_pk_bf16_f32 v113, v92, v93
	v_add_u32_e32 v148, 0x2c000, v147
; __device__ __forceinline__ float fsilu(float x) { return x * fsigmoid(x); }
; __device__ __forceinline__ u32x4 pack8(const f32x4 a, const f32x4 b) { u32x4 w; w.x = cvt_pk_bf16(a[0], a[1]); w.y = cvt_pk_bf16(a[2], a[3]); w.z = cvt_pk_bf16(b[0], b[1]); w.w = cvt_pk_bf16(b[2], b[3]); return w; }
;     __device__ __forceinline__ void operator()(const Acc& acc, const Unit& u, int wr, int wc, int fr, int fq) const {
;     ...
;             for (int m = 0; m < 4; ++m) {
;                 const int row = row0 + ai * HALF + m * 16;
;                 const float r = rsqrtf(sq[ai][m] * (1.0f / D) + EPS);
;                 f32x4 h0, h1;
; #pragma unroll
;                 for (int j = 0; j < 4; ++j) { h0[j] = fsilu(acc[ai][0][m][0][j] * r) * (acc[ai][1][m][0][j] * r); h1[j] = fsilu(acc[ai][0][m][1][j] * r) * (acc[ai][1][m][1][j] * r); }
;                 *(u32x4*)(O + (size_t)row * FF + colh) = pack8(h0, h1);
;             }
	global_store_dwordx4 v148, v[110:113], s[6:7] sc1
	v_pk_mul_f32 v[194:195], v[78:79], v[178:179] op_sel_hi:[1,0]
	v_pk_mul_f32 v[196:197], v[80:81], v[178:179] op_sel_hi:[1,0]
	v_pk_mul_f32 v[198:199], v[66:67], v[178:179] op_sel_hi:[1,0]
	v_pk_mul_f32 v[200:201], v[68:69], v[178:179] op_sel_hi:[1,0]
	v_exp_f32_e32 v194, v194
	v_exp_f32_e32 v195, v195
	v_exp_f32_e32 v196, v196
	v_exp_f32_e32 v197, v197
	v_exp_f32_e32 v198, v198
	v_exp_f32_e32 v199, v199
	v_exp_f32_e32 v200, v200
	v_exp_f32_e32 v201, v201
	v_pk_fma_f32 v[194:195], v[194:195], v[162:163], v[162:163] op_sel_hi:[1,0,0]
	v_pk_fma_f32 v[196:197], v[196:197], v[162:163], v[162:163] op_sel_hi:[1,0,0]
	v_pk_fma_f32 v[198:199], v[198:199], v[162:163], v[162:163] op_sel_hi:[1,0,0]
	v_pk_fma_f32 v[200:201], v[200:201], v[162:163], v[162:163] op_sel_hi:[1,0,0]
	v_rcp_f32_e32 v194, v194
	v_rcp_f32_e32 v195, v195
	v_rcp_f32_e32 v196, v196
	v_rcp_f32_e32 v197, v197
	v_rcp_f32_e32 v198, v198
	v_rcp_f32_e32 v199, v199
	v_rcp_f32_e32 v200, v200
	v_rcp_f32_e32 v201, v201
	v_pk_mul_f32 v[54:55], v[54:55], v[194:195]
	v_pk_mul_f32 v[56:57], v[56:57], v[196:197]
	v_pk_mul_f32 v[50:51], v[50:51], v[198:199]
	v_pk_mul_f32 v[52:53], v[52:53], v[200:201]
	v_cvt_pk_bf16_f32 v78, v54, v55
	v_cvt_pk_bf16_f32 v79, v56, v57
	v_cvt_pk_bf16_f32 v80, v50, v51
	v_cvt_pk_bf16_f32 v81, v52, v53
	v_add_u32_e32 v148, 0x58000, v147
	global_store_dwordx4 v148, v[78:81], s[6:7] sc1
	v_pk_mul_f32 v[194:195], v[38:39], v[184:185] op_sel_hi:[1,0]
	v_pk_mul_f32 v[196:197], v[40:41], v[184:185] op_sel_hi:[1,0]
	v_pk_mul_f32 v[198:199], v[26:27], v[184:185] op_sel_hi:[1,0]
	v_pk_mul_f32 v[200:201], v[28:29], v[184:185] op_sel_hi:[1,0]
	v_exp_f32_e32 v194, v194
	v_exp_f32_e32 v195, v195
	v_exp_f32_e32 v196, v196
	v_exp_f32_e32 v197, v197
	v_exp_f32_e32 v198, v198
	v_exp_f32_e32 v199, v199
	v_exp_f32_e32 v200, v200
	v_exp_f32_e32 v201, v201
	v_pk_fma_f32 v[194:195], v[194:195], v[164:165], v[164:165] op_sel_hi:[1,0,0]
	v_pk_fma_f32 v[196:197], v[196:197], v[164:165], v[164:165] op_sel_hi:[1,0,0]
	v_pk_fma_f32 v[198:199], v[198:199], v[164:165], v[164:165] op_sel_hi:[1,0,0]
	v_pk_fma_f32 v[200:201], v[200:201], v[164:165], v[164:165] op_sel_hi:[1,0,0]
	v_rcp_f32_e32 v194, v194
	v_rcp_f32_e32 v195, v195
	v_rcp_f32_e32 v196, v196
	v_rcp_f32_e32 v197, v197
	v_rcp_f32_e32 v198, v198
	v_rcp_f32_e32 v199, v199
	v_rcp_f32_e32 v200, v200
	v_rcp_f32_e32 v201, v201
	v_pk_mul_f32 v[22:23], v[22:23], v[194:195]
	v_pk_mul_f32 v[24:25], v[24:25], v[196:197]
	v_pk_mul_f32 v[18:19], v[18:19], v[198:199]
	v_pk_mul_f32 v[20:21], v[20:21], v[200:201]
	v_cvt_pk_bf16_f32 v38, v22, v23
	v_cvt_pk_bf16_f32 v39, v24, v25
	v_cvt_pk_bf16_f32 v40, v18, v19
	v_cvt_pk_bf16_f32 v41, v20, v21
	v_add_u32_e32 v148, 0x84000, v147
	global_store_dwordx4 v148, v[38:41], s[6:7] sc1
	v_pk_mul_f32 v[194:195], v[86:87], v[186:187] op_sel_hi:[1,0]
	v_pk_mul_f32 v[196:197], v[88:89], v[186:187] op_sel_hi:[1,0]
	v_pk_mul_f32 v[198:199], v[82:83], v[186:187] op_sel_hi:[1,0]
	v_pk_mul_f32 v[200:201], v[84:85], v[186:187] op_sel_hi:[1,0]
	v_exp_f32_e32 v194, v194
	v_exp_f32_e32 v195, v195
	v_exp_f32_e32 v196, v196
	v_exp_f32_e32 v197, v197
	v_exp_f32_e32 v198, v198
	v_exp_f32_e32 v199, v199
	v_exp_f32_e32 v200, v200
	v_exp_f32_e32 v201, v201
	v_pk_fma_f32 v[194:195], v[194:195], v[166:167], v[166:167] op_sel_hi:[1,0,0]
	v_pk_fma_f32 v[196:197], v[196:197], v[166:167], v[166:167] op_sel_hi:[1,0,0]
	v_pk_fma_f32 v[198:199], v[198:199], v[166:167], v[166:167] op_sel_hi:[1,0,0]
	v_pk_fma_f32 v[200:201], v[200:201], v[166:167], v[166:167] op_sel_hi:[1,0,0]
	v_rcp_f32_e32 v194, v194
	v_rcp_f32_e32 v195, v195
	v_rcp_f32_e32 v196, v196
	v_rcp_f32_e32 v197, v197
	v_rcp_f32_e32 v198, v198
	v_rcp_f32_e32 v199, v199
	v_rcp_f32_e32 v200, v200
	v_rcp_f32_e32 v201, v201
	v_pk_mul_f32 v[102:103], v[102:103], v[194:195]
	v_pk_mul_f32 v[104:105], v[104:105], v[196:197]
	v_pk_mul_f32 v[98:99], v[98:99], v[198:199]
	v_pk_mul_f32 v[100:101], v[100:101], v[200:201]
	v_cvt_pk_bf16_f32 v86, v102, v103
	v_cvt_pk_bf16_f32 v87, v104, v105
	v_cvt_pk_bf16_f32 v88, v98, v99
	v_cvt_pk_bf16_f32 v89, v100, v101
	v_add_u32_e32 v148, 0x160000, v147
	global_store_dwordx4 v148, v[86:89], s[6:7] sc1
	v_pk_mul_f32 v[194:195], v[62:63], v[188:189] op_sel_hi:[1,0]
; __device__ __forceinline__ float fsilu(float x) { return x * fsigmoid(x); }
; __device__ __forceinline__ u32x4 pack8(const f32x4 a, const f32x4 b) { u32x4 w; w.x = cvt_pk_bf16(a[0], a[1]); w.y = cvt_pk_bf16(a[2], a[3]); w.z = cvt_pk_bf16(b[0], b[1]); w.w = cvt_pk_bf16(b[2], b[3]); return w; }
;     __device__ __forceinline__ void operator()(const Acc& acc, const Unit& u, int wr, int wc, int fr, int fq) const {
;     ...
;             for (int m = 0; m < 4; ++m) {
;                 const int row = row0 + ai * HALF + m * 16;
;                 const float r = rsqrtf(sq[ai][m] * (1.0f / D) + EPS);
;                 f32x4 h0, h1;
; #pragma unroll
;                 for (int j = 0; j < 4; ++j) { h0[j] = fsilu(acc[ai][0][m][0][j] * r) * (acc[ai][1][m][0][j] * r); h1[j] = fsilu(acc[ai][0][m][1][j] * r) * (acc[ai][1][m][1][j] * r); }
;                 *(u32x4*)(O + (size_t)row * FF + colh) = pack8(h0, h1);
;             }
	v_pk_mul_f32 v[196:197], v[64:65], v[188:189] op_sel_hi:[1,0]
	v_pk_mul_f32 v[198:199], v[58:59], v[188:189] op_sel_hi:[1,0]
	v_pk_mul_f32 v[200:201], v[60:61], v[188:189] op_sel_hi:[1,0]
	v_exp_f32_e32 v194, v194
	v_exp_f32_e32 v195, v195
	v_exp_f32_e32 v196, v196
	v_exp_f32_e32 v197, v197
	v_exp_f32_e32 v198, v198
	v_exp_f32_e32 v199, v199
	v_exp_f32_e32 v200, v200
	v_exp_f32_e32 v201, v201
	v_pk_fma_f32 v[194:195], v[194:195], v[168:169], v[168:169] op_sel_hi:[1,0,0]
	v_pk_fma_f32 v[196:197], v[196:197], v[168:169], v[168:169] op_sel_hi:[1,0,0]
	v_pk_fma_f32 v[198:199], v[198:199], v[168:169], v[168:169] op_sel_hi:[1,0,0]
	v_pk_fma_f32 v[200:201], v[200:201], v[168:169], v[168:169] op_sel_hi:[1,0,0]
	v_rcp_f32_e32 v194, v194
	v_rcp_f32_e32 v195, v195
	v_rcp_f32_e32 v196, v196
	v_rcp_f32_e32 v197, v197
	v_rcp_f32_e32 v198, v198
	v_rcp_f32_e32 v199, v199
	v_rcp_f32_e32 v200, v200
	v_rcp_f32_e32 v201, v201
	v_pk_mul_f32 v[74:75], v[74:75], v[194:195]
	v_pk_mul_f32 v[76:77], v[76:77], v[196:197]
	v_pk_mul_f32 v[70:71], v[70:71], v[198:199]
	v_pk_mul_f32 v[72:73], v[72:73], v[200:201]
	v_cvt_pk_bf16_f32 v62, v74, v75
	v_cvt_pk_bf16_f32 v63, v76, v77
	v_cvt_pk_bf16_f32 v64, v70, v71
	v_cvt_pk_bf16_f32 v65, v72, v73
	v_add_u32_e32 v148, 0x18c000, v147
	global_store_dwordx4 v148, v[62:65], s[6:7] sc1
	v_pk_mul_f32 v[194:195], v[34:35], v[190:191] op_sel_hi:[1,0]
	v_pk_mul_f32 v[196:197], v[36:37], v[190:191] op_sel_hi:[1,0]
	v_pk_mul_f32 v[198:199], v[30:31], v[190:191] op_sel_hi:[1,0]
	v_pk_mul_f32 v[200:201], v[32:33], v[190:191] op_sel_hi:[1,0]
	v_exp_f32_e32 v194, v194
	v_exp_f32_e32 v195, v195
	v_exp_f32_e32 v196, v196
	v_exp_f32_e32 v197, v197
	v_exp_f32_e32 v198, v198
	v_exp_f32_e32 v199, v199
	v_exp_f32_e32 v200, v200
	v_exp_f32_e32 v201, v201
	v_pk_fma_f32 v[194:195], v[194:195], v[170:171], v[170:171] op_sel_hi:[1,0,0]
	v_pk_fma_f32 v[196:197], v[196:197], v[170:171], v[170:171] op_sel_hi:[1,0,0]
	v_pk_fma_f32 v[198:199], v[198:199], v[170:171], v[170:171] op_sel_hi:[1,0,0]
	v_pk_fma_f32 v[200:201], v[200:201], v[170:171], v[170:171] op_sel_hi:[1,0,0]
	v_rcp_f32_e32 v194, v194
	v_rcp_f32_e32 v195, v195
	v_rcp_f32_e32 v196, v196
	v_rcp_f32_e32 v197, v197
	v_rcp_f32_e32 v198, v198
	v_rcp_f32_e32 v199, v199
	v_rcp_f32_e32 v200, v200
	v_rcp_f32_e32 v201, v201
	v_pk_mul_f32 v[46:47], v[46:47], v[194:195]
	v_pk_mul_f32 v[48:49], v[48:49], v[196:197]
	v_pk_mul_f32 v[42:43], v[42:43], v[198:199]
	v_pk_mul_f32 v[44:45], v[44:45], v[200:201]
	v_cvt_pk_bf16_f32 v34, v46, v47
	v_cvt_pk_bf16_f32 v35, v48, v49
	v_cvt_pk_bf16_f32 v36, v42, v43
	v_cvt_pk_bf16_f32 v37, v44, v45
	v_add_u32_e32 v148, 0x1b8000, v147
	global_store_dwordx4 v148, v[34:37], s[6:7] sc1
	v_pk_mul_f32 v[194:195], v[6:7], v[192:193] op_sel_hi:[1,0]
	v_pk_mul_f32 v[196:197], v[8:9], v[192:193] op_sel_hi:[1,0]
	v_pk_mul_f32 v[198:199], v[2:3], v[192:193] op_sel_hi:[1,0]
	v_pk_mul_f32 v[200:201], v[4:5], v[192:193] op_sel_hi:[1,0]
	v_exp_f32_e32 v194, v194
	v_exp_f32_e32 v195, v195
	v_exp_f32_e32 v196, v196
	v_exp_f32_e32 v197, v197
	v_exp_f32_e32 v198, v198
	v_exp_f32_e32 v199, v199
	v_exp_f32_e32 v200, v200
	v_exp_f32_e32 v201, v201
	v_pk_fma_f32 v[194:195], v[194:195], v[172:173], v[172:173] op_sel_hi:[1,0,0]
	v_pk_fma_f32 v[196:197], v[196:197], v[172:173], v[172:173] op_sel_hi:[1,0,0]
	v_pk_fma_f32 v[198:199], v[198:199], v[172:173], v[172:173] op_sel_hi:[1,0,0]
	v_pk_fma_f32 v[200:201], v[200:201], v[172:173], v[172:173] op_sel_hi:[1,0,0]
	v_rcp_f32_e32 v194, v194
	v_rcp_f32_e32 v195, v195
	v_rcp_f32_e32 v196, v196
	v_rcp_f32_e32 v197, v197
	v_rcp_f32_e32 v198, v198
	v_rcp_f32_e32 v199, v199
	v_rcp_f32_e32 v200, v200
	v_rcp_f32_e32 v201, v201
	v_pk_mul_f32 v[14:15], v[14:15], v[194:195]
	v_pk_mul_f32 v[16:17], v[16:17], v[196:197]
	v_pk_mul_f32 v[10:11], v[10:11], v[198:199]
	v_pk_mul_f32 v[12:13], v[12:13], v[200:201]
	v_cvt_pk_bf16_f32 v6, v14, v15
	v_cvt_pk_bf16_f32 v7, v16, v17
	v_cvt_pk_bf16_f32 v8, v10, v11
	v_cvt_pk_bf16_f32 v9, v12, v13
	v_add_u32_e32 v148, 0x1e4000, v147
	global_store_dwordx4 v148, v[6:9], s[6:7] sc1
	s_andn2_b64 vcc, exec, s[16:17]
	s_mov_b64 s[6:7], -1
	s_cbranch_vccnz .LBB0_160
	s_andn2_b64 vcc, exec, s[4:5]
	s_cbranch_vccnz .LBB0_159
	s_barrier
	s_branch .LBB0_159

; __device__ __forceinline__ void slab_store(const Acc& acc, const Unit& u, float* slab, int wr, int wc, int fr, int fq) {
;     int rowl = wr * 64 + fr, col0 = u.pn * BM + wc * 32 + 8 * fq; asm volatile("" : "+v"(rowl), "+v"(col0));
;     float* base = slab + (size_t)(u.kt0 / u.nkt) * ((size_t)MS * D);
; #pragma unroll
;     for (int m = 0; m < 4; ++m)
; #pragma unroll
;         for (int bj = 0; bj < 2; ++bj) { float* p = base + (size_t)(rowl + m * 16) * D + col0 + bj * HALF; *(f32x4*)p = acc[0][bj][m][0]; *(f32x4*)(p + 4) = acc[0][bj][m][1]; }
; }
.LBB0_251:
	s_and_b64 vcc, exec, s[52:53]
	s_cbranch_vccz .LBB0_275
	s_abs_i32 s37, s33
	s_waitcnt lgkmcnt(0)
	v_cvt_f32_u32_e32 v67, s37
	s_sub_i32 s38, 0, s37
	s_xor_b32 s33, s10, s33
	s_abs_i32 s10, s10
	v_rcp_iflag_f32_e32 v67, v67
	s_ashr_i32 s33, s33, 31
	v_mov_b32_e32 v66, v187
	v_mul_f32_e32 v67, 0x4f7ffffe, v67
	v_cvt_u32_f32_e32 v67, v67
	v_ashrrev_i32_e32 v147, 31, v146
	v_readfirstlane_b32 s39, v67
	s_mul_i32 s38, s38, s39
	s_mul_hi_u32 s38, s39, s38
	s_add_i32 s39, s39, s38
	s_mul_hi_u32 s38, s10, s39
	s_mul_i32 s39, s38, s37
	s_sub_i32 s10, s10, s39
	s_add_i32 s40, s38, 1
	s_sub_i32 s39, s10, s37
	s_cmp_ge_u32 s10, s37
	s_cselect_b32 s38, s40, s38
	s_cselect_b32 s10, s39, s10
	s_add_i32 s39, s38, 1
	s_cmp_ge_u32 s10, s37
	s_cselect_b32 s10, s39, s38
	s_xor_b32 s10, s10, s33
	s_sub_i32 s38, s10, s33
	s_ashr_i32 s39, s38, 31
	s_lshl_b64 s[38:39], s[38:39], 20
	v_readlane_b32 s40, v254, 43
	v_readlane_b32 s41, v254, 44
	s_add_u32 s38, s40, s38
	s_addc_u32 s39, s41, s39
	v_ashrrev_i32_e32 v67, 31, v66
	v_lshl_add_u64 v[68:69], v[146:147], 2, s[38:39]
	v_lshlrev_b64 v[66:67], 13, v[66:67]
	v_lshl_add_u64 v[66:67], v[68:69], 0, v[66:67]
	s_mov_b32 s10, 0x20000
	global_store_dwordx4 v[66:67], v[62:65], off sc1
	global_store_dwordx4 v[66:67], v[58:61], off offset:16 sc1
	global_store_dwordx4 v[66:67], v[42:45], off offset:512 sc1
	global_store_dwordx4 v[66:67], v[34:37], off offset:528 sc1
	s_mov_b64 s[38:39], 0x20000
	s_nop 0
	v_add_co_u32_e32 v36, vcc, s10, v66
	v_lshl_add_u64 v[34:35], v[66:67], 0, s[38:39]
	s_nop 0
	v_addc_co_u32_e32 v37, vcc, 0, v67, vcc
	global_store_dwordx4 v[36:37], v[54:57], off sc1
	global_store_dwordx4 v[34:35], v[50:53], off offset:16 sc1
	global_store_dwordx4 v[34:35], v[26:29], off offset:512 sc1
	global_store_dwordx4 v[34:35], v[18:21], off offset:528 sc1
	s_mov_b64 s[38:39], 0x40000
	s_nop 0
	v_add_co_u32_e32 v20, vcc, 0x40000, v66
	v_lshl_add_u64 v[18:19], v[66:67], 0, s[38:39]
	s_nop 0
	v_addc_co_u32_e32 v21, vcc, 0, v67, vcc
	global_store_dwordx4 v[20:21], v[46:49], off sc1
	global_store_dwordx4 v[18:19], v[38:41], off offset:16 sc1
	global_store_dwordx4 v[18:19], v[14:17], off offset:512 sc1
	global_store_dwordx4 v[18:19], v[10:13], off offset:528 sc1
	s_mov_b64 s[38:39], 0x60000
	s_nop 0
	v_add_co_u32_e32 v12, vcc, 0x60000, v66
	v_lshl_add_u64 v[10:11], v[66:67], 0, s[38:39]
	s_nop 0
	v_addc_co_u32_e32 v13, vcc, 0, v67, vcc
	global_store_dwordx4 v[12:13], v[30:33], off sc1
	global_store_dwordx4 v[10:11], v[22:25], off offset:16 sc1
	global_store_dwordx4 v[10:11], v[6:9], off offset:512 sc1
	global_store_dwordx4 v[10:11], v[2:5], off offset:528 sc1
	s_and_b64 vcc, exec, s[8:9]
	s_mov_b64 s[8:9], -1
	s_cbranch_vccnz .LBB0_230
	s_branch .LBB0_276

; __device__ __forceinline__ u32x4 pack8(const f32x4 a, const f32x4 b) { u32x4 w; w.x = cvt_pk_bf16(a[0], a[1]); w.y = cvt_pk_bf16(a[2], a[3]); w.z = cvt_pk_bf16(b[0], b[1]); w.w = cvt_pk_bf16(b[2], b[3]); return w; }
; __device__ __forceinline__ float dot4(const f32x4 a) { return (a[0] * a[0] + a[1] * a[1]) + (a[2] * a[2] + a[3] * a[3]); }
; __device__ __forceinline__ f32x4 res_lo(const u32x4 w) { return (f32x4){bf_lo(w.x), bf_hi(w.x), bf_lo(w.y), bf_hi(w.y)}; }
; __device__ __forceinline__ f32x4 res_hi(const u32x4 w) { return (f32x4){bf_lo(w.z), bf_hi(w.z), bf_lo(w.w), bf_hi(w.w)}; }
;     __device__ __forceinline__ void operator()(const Acc& acc, const Unit& u, int wr, int wc, int fr, int fq) const {
;     ...
;         int row0 = u.pm * BM + wr * 64 + fr, col0 = u.pn * BM + wc * 32 + 8 * fq; asm volatile("" : "+v"(row0), "+v"(col0));
; #pragma unroll
;         for (int ai = 0; ai < 2; ++ai) {
;             ResHalf res; res_load_half(res, XB, row0 + ai * HALF, col0);
; #pragma unroll
;             for (int m = 0; m < 4; ++m) {
;                 const int row = row0 + ai * HALF + m * 16;
;                 float s = 0.f;
; #pragma unroll
;                 for (int bj = 0; bj < 2; ++bj) {
;                     const f32x4 v0 = res_lo(res[m][bj]) + 0.5f * acc[ai][bj][m][0], v1 = res_hi(res[m][bj]) + 0.5f * acc[ai][bj][m][1];
;                     *(u32x4*)(XB + (size_t)row * D + col0 + bj * HALF) = pack8(v0, v1);
;                     s += dot4(v0) + dot4(v1);
;                 }
;                 s += __shfl_xor(s, 16); s += __shfl_xor(s, 32);
;                 if (fq == 0) atomicAdd(ssq + row, s);
;             }
;         }
.LBB0_258:
	v_lshl_add_u32 v168, s76, 8, v187
	v_mov_b32_e32 v148, v146
	s_nop 0
	v_ashrrev_i32_e32 v149, 31, v148
	v_lshlrev_b64 v[200:201], 1, v[148:149]
	v_ashrrev_i32_e32 v169, 31, v168
	v_lshl_add_u64 v[166:167], s[86:87], 0, v[200:201]
	v_lshlrev_b64 v[202:203], 12, v[168:169]
	v_lshl_add_u64 v[66:67], v[166:167], 0, v[202:203]
	global_load_dwordx4 v[178:181], v[66:67], off
	global_load_dwordx4 v[196:199], v[66:67], off offset:256
	v_add_u32_e32 v174, 16, v168
	v_ashrrev_i32_e32 v175, 31, v174
	v_add_u32_e32 v170, 32, v168
	v_lshlrev_b64 v[176:177], 12, v[174:175]
	v_ashrrev_i32_e32 v171, 31, v170
	v_add_u32_e32 v90, 48, v168
	v_lshl_add_u64 v[66:67], v[166:167], 0, v[176:177]
	v_lshlrev_b64 v[172:173], 12, v[170:171]
	v_ashrrev_i32_e32 v91, 31, v90
	global_load_dwordx4 v[86:89], v[66:67], off
	global_load_dwordx4 v[82:85], v[66:67], off offset:256
	v_lshl_add_u64 v[66:67], v[166:167], 0, v[172:173]
	v_lshlrev_b64 v[92:93], 12, v[90:91]
	global_load_dwordx4 v[78:81], v[66:67], off
	global_load_dwordx4 v[74:77], v[66:67], off offset:256
	v_lshl_add_u64 v[66:67], v[166:167], 0, v[92:93]
	global_load_dwordx4 v[70:73], v[66:67], off
	s_nop 0
	global_load_dwordx4 v[66:69], v[66:67], off offset:256
	v_lshl_add_u64 v[202:203], s[86:87], 0, v[202:203]
	v_lshl_add_u64 v[200:201], v[202:203], 0, v[200:201]
	s_waitcnt vmcnt(7)
	v_lshlrev_b32_e32 v204, 16, v178
	v_and_b32_e32 v205, 0xffff0000, v178
	v_lshlrev_b32_e32 v178, 16, v179
	v_and_b32_e32 v179, 0xffff0000, v179
	v_pk_fma_f32 v[206:207], v[64:65], 0.5, v[178:179] op_sel_hi:[1,0,1]
	v_lshlrev_b32_e32 v178, 16, v180
	v_and_b32_e32 v179, 0xffff0000, v180
	v_pk_fma_f32 v[204:205], v[62:63], 0.5, v[204:205] op_sel_hi:[1,0,1]
	v_lshlrev_b32_e32 v180, 16, v181
	v_and_b32_e32 v181, 0xffff0000, v181
	v_pk_fma_f32 v[212:213], v[58:59], 0.5, v[178:179] op_sel_hi:[1,0,1]
	v_cvt_pk_bf16_f32 v178, v204, v205
	v_pk_fma_f32 v[208:209], v[60:61], 0.5, v[180:181] op_sel_hi:[1,0,1]
	v_cvt_pk_bf16_f32 v179, v206, v207
	v_cvt_pk_bf16_f32 v180, v212, v213
	v_mul_f32_e32 v147, v205, v205
	v_cvt_pk_bf16_f32 v181, v208, v209
	global_store_dwordx4 v[200:201], v[178:181], off sc1
	v_fmac_f32_e32 v147, v204, v204
	s_nop 0
	v_mul_f32_e32 v178, v207, v207
	v_fmac_f32_e32 v178, v206, v206
	v_add_f32_e32 v147, v147, v178
	v_mul_f32_e32 v178, v213, v213
	v_mul_f32_e32 v179, v209, v209
	v_fmac_f32_e32 v178, v212, v212
	v_fmac_f32_e32 v179, v208, v208
	v_add_f32_e32 v178, v178, v179
	v_add_f32_e32 v147, v147, v178
	s_waitcnt vmcnt(7)
	v_lshlrev_b32_e32 v178, 16, v196
	v_and_b32_e32 v179, 0xffff0000, v196
	v_lshlrev_b32_e32 v180, 16, v197
	v_and_b32_e32 v181, 0xffff0000, v197
	v_pk_fma_f32 v[202:203], v[42:43], 0.5, v[178:179] op_sel_hi:[1,0,1]
	v_lshlrev_b32_e32 v178, 16, v198
	v_and_b32_e32 v179, 0xffff0000, v198
	v_pk_fma_f32 v[196:197], v[44:45], 0.5, v[180:181] op_sel_hi:[1,0,1]
	v_lshlrev_b32_e32 v180, 16, v199
	v_and_b32_e32 v181, 0xffff0000, v199
	v_pk_fma_f32 v[204:205], v[34:35], 0.5, v[178:179] op_sel_hi:[1,0,1]
	v_cvt_pk_bf16_f32 v178, v202, v203
	v_cvt_pk_bf16_f32 v179, v196, v197
	v_pk_fma_f32 v[198:199], v[36:37], 0.5, v[180:181] op_sel_hi:[1,0,1]
	v_cvt_pk_bf16_f32 v180, v204, v205
	s_nop 0
	v_cvt_pk_bf16_f32 v181, v198, v199
	global_store_dwordx4 v[200:201], v[178:181], off offset:256 sc1
	s_nop 1
	v_mul_f32_e32 v178, v203, v203
	v_mul_f32_e32 v179, v197, v197
	v_fmac_f32_e32 v178, v202, v202
	v_fmac_f32_e32 v179, v196, v196
	v_add_f32_e32 v178, v178, v179
	v_mul_f32_e32 v179, v205, v205
	v_mul_f32_e32 v180, v199, v199
	v_fmac_f32_e32 v179, v204, v204
	v_fmac_f32_e32 v180, v198, v198
	v_add_f32_e32 v179, v179, v180
	v_add_f32_e32 v178, v178, v179
	v_and_b32_e32 v179, 64, v194
	v_add_f32_e32 v178, v147, v178
	v_xor_b32_e32 v147, 16, v194
	v_add_u32_e32 v179, 64, v179
	v_cmp_lt_i32_e32 vcc, v147, v179
	s_nop 1
	v_cndmask_b32_e32 v147, v194, v147, vcc
	v_lshlrev_b32_e32 v147, 2, v147
	ds_bpermute_b32 v180, v147, v178
	s_waitcnt lgkmcnt(0)
	v_add_f32_e32 v178, v178, v180
	v_xor_b32_e32 v180, 32, v194
	v_cmp_lt_i32_e32 vcc, v180, v179
	s_nop 1
	v_cndmask_b32_e32 v179, v194, v180, vcc
	v_lshlrev_b32_e32 v195, 2, v179
	ds_bpermute_b32 v179, v195, v178
	s_and_saveexec_b64 s[44:45], s[6:7]
	s_cbranch_execz .LBB0_260
	v_lshl_add_u64 v[180:181], v[168:169], 2, s[48:49]
	s_waitcnt lgkmcnt(0)
	v_add_f32_e32 v169, v178, v179
	global_atomic_add_f32 v[180:181], v169, off
; __device__ __forceinline__ u32x4 pack8(const f32x4 a, const f32x4 b) { u32x4 w; w.x = cvt_pk_bf16(a[0], a[1]); w.y = cvt_pk_bf16(a[2], a[3]); w.z = cvt_pk_bf16(b[0], b[1]); w.w = cvt_pk_bf16(b[2], b[3]); return w; }
; __device__ __forceinline__ float dot4(const f32x4 a) { return (a[0] * a[0] + a[1] * a[1]) + (a[2] * a[2] + a[3] * a[3]); }
; __device__ __forceinline__ f32x4 res_lo(const u32x4 w) { return (f32x4){bf_lo(w.x), bf_hi(w.x), bf_lo(w.y), bf_hi(w.y)}; }
; __device__ __forceinline__ f32x4 res_hi(const u32x4 w) { return (f32x4){bf_lo(w.z), bf_hi(w.z), bf_lo(w.w), bf_hi(w.w)}; }
;     __device__ __forceinline__ void operator()(const Acc& acc, const Unit& u, int wr, int wc, int fr, int fq) const {
;     ...
;         int row0 = u.pm * BM + wr * 64 + fr, col0 = u.pn * BM + wc * 32 + 8 * fq; asm volatile("" : "+v"(row0), "+v"(col0));
; #pragma unroll
;         for (int ai = 0; ai < 2; ++ai) {
;             ResHalf res; res_load_half(res, XB, row0 + ai * HALF, col0);
; #pragma unroll
;             for (int m = 0; m < 4; ++m) {
;                 const int row = row0 + ai * HALF + m * 16;
;                 float s = 0.f;
; #pragma unroll
;                 for (int bj = 0; bj < 2; ++bj) {
;                     const f32x4 v0 = res_lo(res[m][bj]) + 0.5f * acc[ai][bj][m][0], v1 = res_hi(res[m][bj]) + 0.5f * acc[ai][bj][m][1];
;                     *(u32x4*)(XB + (size_t)row * D + col0 + bj * HALF) = pack8(v0, v1);
;                     s += dot4(v0) + dot4(v1);
;                 }
;                 s += __shfl_xor(s, 16); s += __shfl_xor(s, 32);
;                 if (fq == 0) atomicAdd(ssq + row, s);
;             }
;         }
.LBB0_260:
	s_or_b64 exec, exec, s[44:45]
	s_waitcnt vmcnt(7)
	v_lshlrev_b32_e32 v178, 16, v86
	s_waitcnt lgkmcnt(0)
	v_and_b32_e32 v179, 0xffff0000, v86
	v_lshlrev_b32_e32 v86, 16, v87
	v_and_b32_e32 v87, 0xffff0000, v87
	v_pk_fma_f32 v[178:179], v[54:55], 0.5, v[178:179] op_sel_hi:[1,0,1]
	v_pk_fma_f32 v[180:181], v[56:57], 0.5, v[86:87] op_sel_hi:[1,0,1]
	v_lshlrev_b32_e32 v86, 16, v88
	v_and_b32_e32 v87, 0xffff0000, v88
	v_mul_f32_e32 v169, v179, v179
	v_lshlrev_b32_e32 v88, 16, v89
	v_and_b32_e32 v89, 0xffff0000, v89
	v_pk_fma_f32 v[198:199], v[50:51], 0.5, v[86:87] op_sel_hi:[1,0,1]
	v_cvt_pk_bf16_f32 v86, v178, v179
	v_fmac_f32_e32 v169, v178, v178
	v_mul_f32_e32 v178, v181, v181
	v_pk_fma_f32 v[196:197], v[52:53], 0.5, v[88:89] op_sel_hi:[1,0,1]
	v_fmac_f32_e32 v178, v180, v180
	v_add_f32_e32 v169, v169, v178
	v_mul_f32_e32 v178, v199, v199
	v_mul_f32_e32 v179, v197, v197
	v_fmac_f32_e32 v178, v198, v198
	v_fmac_f32_e32 v179, v196, v196
	v_add_f32_e32 v178, v178, v179
	v_add_f32_e32 v169, v169, v178
	s_waitcnt vmcnt(6)
	v_lshlrev_b32_e32 v178, 16, v82
	v_and_b32_e32 v179, 0xffff0000, v82
	v_lshlrev_b32_e32 v82, 16, v83
	v_and_b32_e32 v83, 0xffff0000, v83
	v_cvt_pk_bf16_f32 v87, v180, v181
	v_pk_fma_f32 v[180:181], v[28:29], 0.5, v[82:83] op_sel_hi:[1,0,1]
	v_pk_fma_f32 v[82:83], v[26:27], 0.5, v[178:179] op_sel_hi:[1,0,1]
	v_lshlrev_b32_e32 v178, 16, v84
	v_and_b32_e32 v179, 0xffff0000, v84
	v_lshlrev_b32_e32 v84, 16, v85
	v_and_b32_e32 v85, 0xffff0000, v85
	v_cvt_pk_bf16_f32 v89, v196, v197
	v_pk_fma_f32 v[196:197], v[20:21], 0.5, v[84:85] op_sel_hi:[1,0,1]
	v_mul_f32_e32 v84, v83, v83
	v_mul_f32_e32 v85, v181, v181
	v_pk_fma_f32 v[178:179], v[18:19], 0.5, v[178:179] op_sel_hi:[1,0,1]
	v_fmac_f32_e32 v84, v82, v82
	v_fmac_f32_e32 v85, v180, v180
	v_cvt_pk_bf16_f32 v88, v198, v199
	v_add_f32_e32 v84, v84, v85
	v_mul_f32_e32 v85, v179, v179
	v_mul_f32_e32 v198, v197, v197
	v_fmac_f32_e32 v85, v178, v178
	v_fmac_f32_e32 v198, v196, v196
	v_add_f32_e32 v85, v85, v198
	v_add_f32_e32 v84, v84, v85
	v_add_f32_e32 v169, v169, v84
	ds_bpermute_b32 v198, v147, v169
	v_lshl_add_u64 v[84:85], s[86:87], 0, v[176:177]
	v_lshl_add_u64 v[176:177], v[148:149], 1, v[84:85]
	v_cvt_pk_bf16_f32 v84, v82, v83
	global_store_dwordx4 v[176:177], v[86:89], off sc1
	s_waitcnt lgkmcnt(0)
	v_add_f32_e32 v82, v169, v198
	ds_bpermute_b32 v83, v195, v82
	v_cvt_pk_bf16_f32 v85, v180, v181
	v_cvt_pk_bf16_f32 v86, v178, v179
	v_cvt_pk_bf16_f32 v87, v196, v197
	global_store_dwordx4 v[176:177], v[84:87], off offset:256 sc1
	s_and_saveexec_b64 s[44:45], s[6:7]
	s_cbranch_execz .LBB0_262
	v_lshl_add_u64 v[84:85], v[174:175], 2, s[48:49]
	s_waitcnt lgkmcnt(0)
	v_add_f32_e32 v82, v82, v83
	global_atomic_add_f32 v[84:85], v82, off
.LBB0_262:
	s_or_b64 exec, exec, s[44:45]
	s_waitcnt vmcnt(7)
	v_lshlrev_b32_e32 v82, 16, v78
	s_waitcnt lgkmcnt(0)
	v_and_b32_e32 v83, 0xffff0000, v78
	v_lshlrev_b32_e32 v78, 16, v79
	v_and_b32_e32 v79, 0xffff0000, v79
	v_pk_fma_f32 v[84:85], v[48:49], 0.5, v[78:79] op_sel_hi:[1,0,1]
	v_pk_fma_f32 v[82:83], v[46:47], 0.5, v[82:83] op_sel_hi:[1,0,1]
	v_lshlrev_b32_e32 v78, 16, v80
	v_and_b32_e32 v79, 0xffff0000, v80
	v_pk_fma_f32 v[88:89], v[38:39], 0.5, v[78:79] op_sel_hi:[1,0,1]
	v_cvt_pk_bf16_f32 v78, v82, v83
	v_mul_f32_e32 v83, v83, v83
	v_lshlrev_b32_e32 v80, 16, v81
	v_and_b32_e32 v81, 0xffff0000, v81
	v_fmac_f32_e32 v83, v82, v82
	v_mul_f32_e32 v82, v85, v85
	v_pk_fma_f32 v[86:87], v[40:41], 0.5, v[80:81] op_sel_hi:[1,0,1]
	v_fmac_f32_e32 v82, v84, v84
	v_cvt_pk_bf16_f32 v79, v84, v85
	v_add_f32_e32 v82, v83, v82
	v_mul_f32_e32 v83, v89, v89
	v_mul_f32_e32 v84, v87, v87
	v_fmac_f32_e32 v83, v88, v88
	v_fmac_f32_e32 v84, v86, v86
	v_add_f32_e32 v83, v83, v84
	v_cvt_pk_bf16_f32 v80, v88, v89
	v_add_f32_e32 v88, v82, v83
	s_waitcnt vmcnt(6)
	v_lshlrev_b32_e32 v82, 16, v74
	v_and_b32_e32 v83, 0xffff0000, v74
	v_lshlrev_b32_e32 v74, 16, v75
	v_and_b32_e32 v75, 0xffff0000, v75
	v_pk_fma_f32 v[84:85], v[16:17], 0.5, v[74:75] op_sel_hi:[1,0,1]
	v_pk_fma_f32 v[74:75], v[14:15], 0.5, v[82:83] op_sel_hi:[1,0,1]
	v_lshlrev_b32_e32 v82, 16, v76
	v_and_b32_e32 v83, 0xffff0000, v76
	v_lshlrev_b32_e32 v76, 16, v77
	v_and_b32_e32 v77, 0xffff0000, v77
	v_cvt_pk_bf16_f32 v81, v86, v87
	v_pk_fma_f32 v[86:87], v[12:13], 0.5, v[76:77] op_sel_hi:[1,0,1]
	v_mul_f32_e32 v76, v75, v75
	v_mul_f32_e32 v77, v85, v85
	v_pk_fma_f32 v[82:83], v[10:11], 0.5, v[82:83] op_sel_hi:[1,0,1]
	v_fmac_f32_e32 v76, v74, v74
	v_fmac_f32_e32 v77, v84, v84
	v_add_f32_e32 v76, v76, v77
	v_mul_f32_e32 v77, v83, v83
	v_mul_f32_e32 v89, v87, v87
	v_fmac_f32_e32 v77, v82, v82
	v_fmac_f32_e32 v89, v86, v86
	v_add_f32_e32 v77, v77, v89
	v_add_f32_e32 v76, v76, v77
	v_add_f32_e32 v169, v88, v76
	ds_bpermute_b32 v174, v147, v169
	v_lshl_add_u64 v[76:77], s[86:87], 0, v[172:173]
	v_lshl_add_u64 v[88:89], v[148:149], 1, v[76:77]
	v_cvt_pk_bf16_f32 v76, v74, v75
	global_store_dwordx4 v[88:89], v[78:81], off sc1
	s_waitcnt lgkmcnt(0)
	v_add_f32_e32 v74, v169, v174
	ds_bpermute_b32 v75, v195, v74
	v_cvt_pk_bf16_f32 v77, v84, v85
	v_cvt_pk_bf16_f32 v78, v82, v83
	v_cvt_pk_bf16_f32 v79, v86, v87
	global_store_dwordx4 v[88:89], v[76:79], off offset:256 sc1
	s_and_saveexec_b64 s[44:45], s[6:7]
	s_cbranch_execz .LBB0_264
	v_lshl_add_u64 v[76:77], v[170:171], 2, s[48:49]
	s_waitcnt lgkmcnt(0)
	v_add_f32_e32 v74, v74, v75
	global_atomic_add_f32 v[76:77], v74, off
; __device__ __forceinline__ u32x4 pack8(const f32x4 a, const f32x4 b) { u32x4 w; w.x = cvt_pk_bf16(a[0], a[1]); w.y = cvt_pk_bf16(a[2], a[3]); w.z = cvt_pk_bf16(b[0], b[1]); w.w = cvt_pk_bf16(b[2], b[3]); return w; }
; __device__ __forceinline__ float dot4(const f32x4 a) { return (a[0] * a[0] + a[1] * a[1]) + (a[2] * a[2] + a[3] * a[3]); }
; __device__ __forceinline__ f32x4 res_lo(const u32x4 w) { return (f32x4){bf_lo(w.x), bf_hi(w.x), bf_lo(w.y), bf_hi(w.y)}; }
; __device__ __forceinline__ f32x4 res_hi(const u32x4 w) { return (f32x4){bf_lo(w.z), bf_hi(w.z), bf_lo(w.w), bf_hi(w.w)}; }
;     __device__ __forceinline__ void operator()(const Acc& acc, const Unit& u, int wr, int wc, int fr, int fq) const {
;     ...
;         int row0 = u.pm * BM + wr * 64 + fr, col0 = u.pn * BM + wc * 32 + 8 * fq; asm volatile("" : "+v"(row0), "+v"(col0));
; #pragma unroll
;         for (int ai = 0; ai < 2; ++ai) {
;             ResHalf res; res_load_half(res, XB, row0 + ai * HALF, col0);
; #pragma unroll
;             for (int m = 0; m < 4; ++m) {
;                 const int row = row0 + ai * HALF + m * 16;
;                 float s = 0.f;
; #pragma unroll
;                 for (int bj = 0; bj < 2; ++bj) {
;                     const f32x4 v0 = res_lo(res[m][bj]) + 0.5f * acc[ai][bj][m][0], v1 = res_hi(res[m][bj]) + 0.5f * acc[ai][bj][m][1];
;                     *(u32x4*)(XB + (size_t)row * D + col0 + bj * HALF) = pack8(v0, v1);
;                     s += dot4(v0) + dot4(v1);
;                 }
;                 s += __shfl_xor(s, 16); s += __shfl_xor(s, 32);
;                 if (fq == 0) atomicAdd(ssq + row, s);
;             }
;         }
.LBB0_264:
	s_or_b64 exec, exec, s[44:45]
	s_waitcnt vmcnt(7)
	v_lshlrev_b32_e32 v74, 16, v70
	s_waitcnt lgkmcnt(0)
	v_and_b32_e32 v75, 0xffff0000, v70
	v_lshlrev_b32_e32 v70, 16, v71
	v_and_b32_e32 v71, 0xffff0000, v71
	v_pk_fma_f32 v[76:77], v[32:33], 0.5, v[70:71] op_sel_hi:[1,0,1]
	v_pk_fma_f32 v[74:75], v[30:31], 0.5, v[74:75] op_sel_hi:[1,0,1]
	v_lshlrev_b32_e32 v70, 16, v72
	v_and_b32_e32 v71, 0xffff0000, v72
	v_pk_fma_f32 v[80:81], v[22:23], 0.5, v[70:71] op_sel_hi:[1,0,1]
	v_cvt_pk_bf16_f32 v70, v74, v75
	v_mul_f32_e32 v75, v75, v75
	v_lshlrev_b32_e32 v72, 16, v73
	v_and_b32_e32 v73, 0xffff0000, v73
	v_fmac_f32_e32 v75, v74, v74
	v_mul_f32_e32 v74, v77, v77
	v_pk_fma_f32 v[78:79], v[24:25], 0.5, v[72:73] op_sel_hi:[1,0,1]
	v_fmac_f32_e32 v74, v76, v76
	v_cvt_pk_bf16_f32 v71, v76, v77
	v_add_f32_e32 v74, v75, v74
	v_mul_f32_e32 v75, v81, v81
	v_mul_f32_e32 v76, v79, v79
	v_fmac_f32_e32 v75, v80, v80
	v_fmac_f32_e32 v76, v78, v78
	v_add_f32_e32 v75, v75, v76
	v_cvt_pk_bf16_f32 v72, v80, v81
	v_add_f32_e32 v80, v74, v75
	s_waitcnt vmcnt(6)
	v_lshlrev_b32_e32 v74, 16, v66
	v_and_b32_e32 v75, 0xffff0000, v66
	v_lshlrev_b32_e32 v66, 16, v67
	v_and_b32_e32 v67, 0xffff0000, v67
	v_pk_fma_f32 v[76:77], v[8:9], 0.5, v[66:67] op_sel_hi:[1,0,1]
	v_pk_fma_f32 v[66:67], v[6:7], 0.5, v[74:75] op_sel_hi:[1,0,1]
	v_lshlrev_b32_e32 v74, 16, v68
	v_and_b32_e32 v75, 0xffff0000, v68
	v_lshlrev_b32_e32 v68, 16, v69
	v_and_b32_e32 v69, 0xffff0000, v69
	v_cvt_pk_bf16_f32 v73, v78, v79
	v_pk_fma_f32 v[78:79], v[4:5], 0.5, v[68:69] op_sel_hi:[1,0,1]
	v_mul_f32_e32 v68, v67, v67
	v_mul_f32_e32 v69, v77, v77
	v_pk_fma_f32 v[74:75], v[2:3], 0.5, v[74:75] op_sel_hi:[1,0,1]
	v_fmac_f32_e32 v68, v66, v66
	v_fmac_f32_e32 v69, v76, v76
	v_add_f32_e32 v68, v68, v69
	v_mul_f32_e32 v69, v75, v75
	v_mul_f32_e32 v81, v79, v79
	v_fmac_f32_e32 v69, v74, v74
	v_fmac_f32_e32 v81, v78, v78
	v_add_f32_e32 v69, v69, v81
	v_add_f32_e32 v68, v68, v69
	v_add_f32_e32 v82, v80, v68
	ds_bpermute_b32 v83, v147, v82
	v_lshl_add_u64 v[68:69], s[86:87], 0, v[92:93]
	v_lshl_add_u64 v[80:81], v[148:149], 1, v[68:69]
	v_cvt_pk_bf16_f32 v68, v66, v67
	global_store_dwordx4 v[80:81], v[70:73], off sc1
	s_waitcnt lgkmcnt(0)
	v_add_f32_e32 v66, v82, v83
	ds_bpermute_b32 v67, v195, v66
	v_cvt_pk_bf16_f32 v69, v76, v77
	v_cvt_pk_bf16_f32 v70, v74, v75
	v_cvt_pk_bf16_f32 v71, v78, v79
	global_store_dwordx4 v[80:81], v[68:71], off offset:256 sc1
	s_and_saveexec_b64 s[44:45], s[6:7]
	s_cbranch_execz .LBB0_266
	v_lshl_add_u64 v[68:69], v[90:91], 2, s[48:49]
	s_waitcnt lgkmcnt(0)
	v_add_f32_e32 v66, v66, v67
	global_atomic_add_f32 v[68:69], v66, off
.LBB0_266:
	s_or_b64 exec, exec, s[44:45]
	v_add_u32_e32 v180, 0x80, v168
	v_ashrrev_i32_e32 v181, 31, v180
	v_lshlrev_b64 v[200:201], 12, v[180:181]
	s_waitcnt lgkmcnt(0)
	v_lshl_add_u64 v[66:67], v[166:167], 0, v[200:201]
	global_load_dwordx4 v[196:199], v[66:67], off
	global_load_dwordx4 v[90:93], v[66:67], off offset:256
	v_add_u32_e32 v176, 0x90, v168
	v_ashrrev_i32_e32 v177, 31, v176
	v_add_u32_e32 v172, 0xa0, v168
	v_lshlrev_b64 v[178:179], 12, v[176:177]
	v_ashrrev_i32_e32 v173, 31, v172
	v_add_u32_e32 v168, 0xb0, v168
	v_lshl_add_u64 v[66:67], v[166:167], 0, v[178:179]
	v_lshlrev_b64 v[174:175], 12, v[172:173]
	v_ashrrev_i32_e32 v169, 31, v168
	global_load_dwordx4 v[86:89], v[66:67], off
	global_load_dwordx4 v[82:85], v[66:67], off offset:256
	v_lshl_add_u64 v[66:67], v[166:167], 0, v[174:175]
	v_lshlrev_b64 v[170:171], 12, v[168:169]
	global_load_dwordx4 v[78:81], v[66:67], off
	global_load_dwordx4 v[74:77], v[66:67], off offset:256
	v_lshl_add_u64 v[66:67], v[166:167], 0, v[170:171]
	global_load_dwordx4 v[70:73], v[66:67], off
	s_nop 0
	global_load_dwordx4 v[66:69], v[66:67], off offset:256
	s_waitcnt vmcnt(7)
	v_lshlrev_b32_e32 v166, 16, v196
	v_and_b32_e32 v167, 0xffff0000, v196
	v_lshlrev_b32_e32 v196, 16, v197
	v_and_b32_e32 v197, 0xffff0000, v197
	v_pk_add_f32 v[162:163], v[162:163], v[196:197]
	v_pk_add_f32 v[164:165], v[164:165], v[166:167]
	v_lshlrev_b32_e32 v166, 16, v198
	v_and_b32_e32 v167, 0xffff0000, v198
	v_lshlrev_b32_e32 v196, 16, v199
	v_and_b32_e32 v197, 0xffff0000, v199
	v_lshl_add_u64 v[198:199], s[86:87], 0, v[200:201]
	v_pk_add_f32 v[196:197], v[158:159], v[196:197]
	v_cvt_pk_bf16_f32 v158, v164, v165
	v_cvt_pk_bf16_f32 v159, v162, v163
	v_lshl_add_u64 v[198:199], v[148:149], 1, v[198:199]
	v_pk_add_f32 v[166:167], v[160:161], v[166:167]
	v_cvt_pk_bf16_f32 v161, v196, v197
	s_nop 0
	v_cvt_pk_bf16_f32 v160, v166, v167
	global_store_dwordx4 v[198:199], v[158:161], off sc1
	s_nop 1
	v_mul_f32_e32 v158, v165, v165
	v_mul_f32_e32 v159, v163, v163
	v_fmac_f32_e32 v158, v164, v164
	v_fmac_f32_e32 v159, v162, v162
	v_add_f32_e32 v158, v158, v159
	v_mul_f32_e32 v159, v167, v167
	v_mul_f32_e32 v160, v197, v197
	v_fmac_f32_e32 v159, v166, v166
	v_fmac_f32_e32 v160, v196, v196
	v_add_f32_e32 v159, v159, v160
	v_add_f32_e32 v160, v158, v159
	s_waitcnt vmcnt(7)
	v_lshlrev_b32_e32 v158, 16, v90
	v_and_b32_e32 v159, 0xffff0000, v90
	v_lshlrev_b32_e32 v90, 16, v91
	v_and_b32_e32 v91, 0xffff0000, v91
	v_pk_add_f32 v[154:155], v[154:155], v[90:91]
	v_lshlrev_b32_e32 v90, 16, v92
	v_and_b32_e32 v91, 0xffff0000, v92
	v_pk_add_f32 v[156:157], v[156:157], v[158:159]
	v_lshlrev_b32_e32 v92, 16, v93
	v_and_b32_e32 v93, 0xffff0000, v93
	v_pk_add_f32 v[150:151], v[150:151], v[90:91]
	v_cvt_pk_bf16_f32 v90, v156, v157
	v_cvt_pk_bf16_f32 v91, v154, v155
	v_pk_add_f32 v[152:153], v[152:153], v[92:93]
	v_cvt_pk_bf16_f32 v92, v150, v151
	s_nop 0
	v_cvt_pk_bf16_f32 v93, v152, v153
	global_store_dwordx4 v[198:199], v[90:93], off offset:256 sc1
	s_nop 1
	v_mul_f32_e32 v90, v157, v157
	v_mul_f32_e32 v91, v155, v155
	v_fmac_f32_e32 v90, v156, v156
	v_fmac_f32_e32 v91, v154, v154
	v_add_f32_e32 v90, v90, v91
	v_mul_f32_e32 v91, v151, v151
	v_mul_f32_e32 v92, v153, v153
	v_fmac_f32_e32 v91, v150, v150
	v_fmac_f32_e32 v92, v152, v152
	v_add_f32_e32 v91, v91, v92
	v_add_f32_e32 v90, v90, v91
	v_add_f32_e32 v90, v160, v90
	ds_bpermute_b32 v91, v147, v90
	s_waitcnt lgkmcnt(0)
	v_add_f32_e32 v90, v90, v91
	ds_bpermute_b32 v91, v195, v90
	s_and_saveexec_b64 s[44:45], s[6:7]
	s_cbranch_execz .LBB0_268
	v_lshl_add_u64 v[92:93], v[180:181], 2, s[48:49]
	s_waitcnt lgkmcnt(0)
	v_add_f32_e32 v90, v90, v91
	global_atomic_add_f32 v[92:93], v90, off
; __device__ __forceinline__ u32x4 pack8(const f32x4 a, const f32x4 b) { u32x4 w; w.x = cvt_pk_bf16(a[0], a[1]); w.y = cvt_pk_bf16(a[2], a[3]); w.z = cvt_pk_bf16(b[0], b[1]); w.w = cvt_pk_bf16(b[2], b[3]); return w; }
; __device__ __forceinline__ float dot4(const f32x4 a) { return (a[0] * a[0] + a[1] * a[1]) + (a[2] * a[2] + a[3] * a[3]); }
; __device__ __forceinline__ f32x4 res_lo(const u32x4 w) { return (f32x4){bf_lo(w.x), bf_hi(w.x), bf_lo(w.y), bf_hi(w.y)}; }
; __device__ __forceinline__ f32x4 res_hi(const u32x4 w) { return (f32x4){bf_lo(w.z), bf_hi(w.z), bf_lo(w.w), bf_hi(w.w)}; }
;     __device__ __forceinline__ void operator()(const Acc& acc, const Unit& u, int wr, int wc, int fr, int fq) const {
;     ...
;         int row0 = u.pm * BM + wr * 64 + fr, col0 = u.pn * BM + wc * 32 + 8 * fq; asm volatile("" : "+v"(row0), "+v"(col0));
; #pragma unroll
;         for (int ai = 0; ai < 2; ++ai) {
;             ResHalf res; res_load_half(res, XB, row0 + ai * HALF, col0);
; #pragma unroll
;             for (int m = 0; m < 4; ++m) {
;                 const int row = row0 + ai * HALF + m * 16;
;                 float s = 0.f;
; #pragma unroll
;                 for (int bj = 0; bj < 2; ++bj) {
;                     const f32x4 v0 = res_lo(res[m][bj]) + 0.5f * acc[ai][bj][m][0], v1 = res_hi(res[m][bj]) + 0.5f * acc[ai][bj][m][1];
;                     *(u32x4*)(XB + (size_t)row * D + col0 + bj * HALF) = pack8(v0, v1);
;                     s += dot4(v0) + dot4(v1);
;                 }
;                 s += __shfl_xor(s, 16); s += __shfl_xor(s, 32);
;                 if (fq == 0) atomicAdd(ssq + row, s);
;             }
;         }
.LBB0_268:
	s_or_b64 exec, exec, s[44:45]
	s_waitcnt vmcnt(7)
	v_lshlrev_b32_e32 v90, 16, v86
	s_waitcnt lgkmcnt(0)
	v_and_b32_e32 v91, 0xffff0000, v86
	v_lshlrev_b32_e32 v86, 16, v87
	v_and_b32_e32 v87, 0xffff0000, v87
	v_pk_add_f32 v[92:93], v[136:137], v[86:87]
	v_pk_add_f32 v[90:91], v[134:135], v[90:91]
	v_lshlrev_b32_e32 v86, 16, v88
	v_and_b32_e32 v87, 0xffff0000, v88
	v_pk_add_f32 v[126:127], v[126:127], v[86:87]
	v_cvt_pk_bf16_f32 v86, v90, v91
	v_mul_f32_e32 v91, v91, v91
	v_lshlrev_b32_e32 v88, 16, v89
	v_and_b32_e32 v89, 0xffff0000, v89
	v_fmac_f32_e32 v91, v90, v90
	v_mul_f32_e32 v90, v93, v93
	v_pk_add_f32 v[128:129], v[128:129], v[88:89]
	v_fmac_f32_e32 v90, v92, v92
	v_cvt_pk_bf16_f32 v87, v92, v93
	v_add_f32_e32 v90, v91, v90
	v_mul_f32_e32 v91, v127, v127
	v_mul_f32_e32 v92, v129, v129
	v_fmac_f32_e32 v91, v126, v126
	v_fmac_f32_e32 v92, v128, v128
	v_add_f32_e32 v91, v91, v92
	v_cvt_pk_bf16_f32 v89, v128, v129
	v_add_f32_e32 v128, v90, v91
	s_waitcnt vmcnt(6)
	v_lshlrev_b32_e32 v90, 16, v82
	v_and_b32_e32 v91, 0xffff0000, v82
	v_lshlrev_b32_e32 v82, 16, v83
	v_and_b32_e32 v83, 0xffff0000, v83
	v_pk_add_f32 v[92:93], v[144:145], v[82:83]
	v_pk_add_f32 v[82:83], v[142:143], v[90:91]
	v_lshlrev_b32_e32 v90, 16, v84
	v_and_b32_e32 v91, 0xffff0000, v84
	v_lshlrev_b32_e32 v84, 16, v85
	v_and_b32_e32 v85, 0xffff0000, v85
	v_cvt_pk_bf16_f32 v88, v126, v127
	v_pk_add_f32 v[126:127], v[140:141], v[84:85]
	v_mul_f32_e32 v84, v83, v83
	v_mul_f32_e32 v85, v93, v93
	v_pk_add_f32 v[90:91], v[138:139], v[90:91]
	v_fmac_f32_e32 v84, v82, v82
	v_fmac_f32_e32 v85, v92, v92
	v_add_f32_e32 v84, v84, v85
	v_mul_f32_e32 v85, v91, v91
	v_mul_f32_e32 v129, v127, v127
	v_fmac_f32_e32 v85, v90, v90
	v_fmac_f32_e32 v129, v126, v126
	v_add_f32_e32 v85, v85, v129
	v_add_f32_e32 v84, v84, v85
	v_add_f32_e32 v134, v128, v84
	ds_bpermute_b32 v135, v147, v134
	v_lshl_add_u64 v[84:85], s[86:87], 0, v[178:179]
	v_lshl_add_u64 v[128:129], v[148:149], 1, v[84:85]
	v_cvt_pk_bf16_f32 v84, v82, v83
	global_store_dwordx4 v[128:129], v[86:89], off sc1
	s_waitcnt lgkmcnt(0)
	v_add_f32_e32 v82, v134, v135
	ds_bpermute_b32 v83, v195, v82
	v_cvt_pk_bf16_f32 v85, v92, v93
	v_cvt_pk_bf16_f32 v86, v90, v91
	v_cvt_pk_bf16_f32 v87, v126, v127
	global_store_dwordx4 v[128:129], v[84:87], off offset:256 sc1
	s_and_saveexec_b64 s[44:45], s[6:7]
	s_cbranch_execz .LBB0_270
	v_lshl_add_u64 v[84:85], v[176:177], 2, s[48:49]
	s_waitcnt lgkmcnt(0)
	v_add_f32_e32 v82, v82, v83
	global_atomic_add_f32 v[84:85], v82, off
; __device__ __forceinline__ u32x4 pack8(const f32x4 a, const f32x4 b) { u32x4 w; w.x = cvt_pk_bf16(a[0], a[1]); w.y = cvt_pk_bf16(a[2], a[3]); w.z = cvt_pk_bf16(b[0], b[1]); w.w = cvt_pk_bf16(b[2], b[3]); return w; }
; __device__ __forceinline__ float dot4(const f32x4 a) { return (a[0] * a[0] + a[1] * a[1]) + (a[2] * a[2] + a[3] * a[3]); }
; __device__ __forceinline__ f32x4 res_lo(const u32x4 w) { return (f32x4){bf_lo(w.x), bf_hi(w.x), bf_lo(w.y), bf_hi(w.y)}; }
; __device__ __forceinline__ f32x4 res_hi(const u32x4 w) { return (f32x4){bf_lo(w.z), bf_hi(w.z), bf_lo(w.w), bf_hi(w.w)}; }
;     __device__ __forceinline__ void operator()(const Acc& acc, const Unit& u, int wr, int wc, int fr, int fq) const {
;     ...
;         int row0 = u.pm * BM + wr * 64 + fr, col0 = u.pn * BM + wc * 32 + 8 * fq; asm volatile("" : "+v"(row0), "+v"(col0));
; #pragma unroll
;         for (int ai = 0; ai < 2; ++ai) {
;             ResHalf res; res_load_half(res, XB, row0 + ai * HALF, col0);
; #pragma unroll
;             for (int m = 0; m < 4; ++m) {
;                 const int row = row0 + ai * HALF + m * 16;
;                 float s = 0.f;
; #pragma unroll
;                 for (int bj = 0; bj < 2; ++bj) {
;                     const f32x4 v0 = res_lo(res[m][bj]) + 0.5f * acc[ai][bj][m][0], v1 = res_hi(res[m][bj]) + 0.5f * acc[ai][bj][m][1];
;                     *(u32x4*)(XB + (size_t)row * D + col0 + bj * HALF) = pack8(v0, v1);
;                     s += dot4(v0) + dot4(v1);
;                 }
;                 s += __shfl_xor(s, 16); s += __shfl_xor(s, 32);
;                 if (fq == 0) atomicAdd(ssq + row, s);
;             }
;         }
.LBB0_270:
	s_or_b64 exec, exec, s[44:45]
	s_waitcnt vmcnt(7)
	v_lshlrev_b32_e32 v82, 16, v78
	s_waitcnt lgkmcnt(0)
	v_and_b32_e32 v83, 0xffff0000, v78
	v_lshlrev_b32_e32 v78, 16, v79
	v_and_b32_e32 v79, 0xffff0000, v79
	v_pk_add_f32 v[84:85], v[116:117], v[78:79]
	v_pk_add_f32 v[82:83], v[114:115], v[82:83]
	v_lshlrev_b32_e32 v78, 16, v80
	v_and_b32_e32 v79, 0xffff0000, v80
	v_pk_add_f32 v[88:89], v[110:111], v[78:79]
	v_cvt_pk_bf16_f32 v78, v82, v83
	v_mul_f32_e32 v83, v83, v83
	v_lshlrev_b32_e32 v80, 16, v81
	v_and_b32_e32 v81, 0xffff0000, v81
	v_fmac_f32_e32 v83, v82, v82
	v_mul_f32_e32 v82, v85, v85
	v_pk_add_f32 v[86:87], v[112:113], v[80:81]
	v_fmac_f32_e32 v82, v84, v84
	v_cvt_pk_bf16_f32 v79, v84, v85
	v_add_f32_e32 v82, v83, v82
	v_mul_f32_e32 v83, v89, v89
	v_mul_f32_e32 v84, v87, v87
	v_fmac_f32_e32 v83, v88, v88
	v_fmac_f32_e32 v84, v86, v86
	v_add_f32_e32 v83, v83, v84
	v_cvt_pk_bf16_f32 v80, v88, v89
	v_add_f32_e32 v88, v82, v83
	s_waitcnt vmcnt(6)
	v_lshlrev_b32_e32 v82, 16, v74
	v_and_b32_e32 v83, 0xffff0000, v74
	v_lshlrev_b32_e32 v74, 16, v75
	v_and_b32_e32 v75, 0xffff0000, v75
	v_pk_add_f32 v[84:85], v[124:125], v[74:75]
	v_pk_add_f32 v[74:75], v[122:123], v[82:83]
	v_lshlrev_b32_e32 v82, 16, v76
	v_and_b32_e32 v83, 0xffff0000, v76
	v_lshlrev_b32_e32 v76, 16, v77
	v_and_b32_e32 v77, 0xffff0000, v77
	v_cvt_pk_bf16_f32 v81, v86, v87
	v_pk_add_f32 v[86:87], v[120:121], v[76:77]
	v_mul_f32_e32 v76, v75, v75
	v_mul_f32_e32 v77, v85, v85
	v_pk_add_f32 v[82:83], v[118:119], v[82:83]
	v_fmac_f32_e32 v76, v74, v74
	v_fmac_f32_e32 v77, v84, v84
	v_add_f32_e32 v76, v76, v77
	v_mul_f32_e32 v77, v83, v83
	v_mul_f32_e32 v89, v87, v87
	v_fmac_f32_e32 v77, v82, v82
	v_fmac_f32_e32 v89, v86, v86
	v_add_f32_e32 v77, v77, v89
	v_add_f32_e32 v76, v76, v77
	v_add_f32_e32 v90, v88, v76
	ds_bpermute_b32 v91, v147, v90
	v_lshl_add_u64 v[76:77], s[86:87], 0, v[174:175]
	v_lshl_add_u64 v[88:89], v[148:149], 1, v[76:77]
	v_cvt_pk_bf16_f32 v76, v74, v75
	global_store_dwordx4 v[88:89], v[78:81], off sc1
	s_waitcnt lgkmcnt(0)
	v_add_f32_e32 v74, v90, v91
	ds_bpermute_b32 v75, v195, v74
	v_cvt_pk_bf16_f32 v77, v84, v85
	v_cvt_pk_bf16_f32 v78, v82, v83
	v_cvt_pk_bf16_f32 v79, v86, v87
	global_store_dwordx4 v[88:89], v[76:79], off offset:256 sc1
	s_and_saveexec_b64 s[44:45], s[6:7]
	s_cbranch_execz .LBB0_272
	v_lshl_add_u64 v[76:77], v[172:173], 2, s[48:49]
	s_waitcnt lgkmcnt(0)
	v_add_f32_e32 v74, v74, v75
	global_atomic_add_f32 v[76:77], v74, off
.LBB0_272:
	s_or_b64 exec, exec, s[44:45]
	s_waitcnt vmcnt(7)
	v_lshlrev_b32_e32 v74, 16, v70
	s_waitcnt lgkmcnt(0)
	v_and_b32_e32 v75, 0xffff0000, v70
	v_lshlrev_b32_e32 v70, 16, v71
	v_and_b32_e32 v71, 0xffff0000, v71
	v_pk_add_f32 v[76:77], v[100:101], v[70:71]
	v_pk_add_f32 v[74:75], v[98:99], v[74:75]
	v_lshlrev_b32_e32 v70, 16, v72
	v_and_b32_e32 v71, 0xffff0000, v72
	v_pk_add_f32 v[80:81], v[94:95], v[70:71]
	v_cvt_pk_bf16_f32 v70, v74, v75
	v_mul_f32_e32 v75, v75, v75
	v_lshlrev_b32_e32 v72, 16, v73
	v_and_b32_e32 v73, 0xffff0000, v73
	v_fmac_f32_e32 v75, v74, v74
	v_mul_f32_e32 v74, v77, v77
	v_pk_add_f32 v[78:79], v[96:97], v[72:73]
	v_fmac_f32_e32 v74, v76, v76
	v_cvt_pk_bf16_f32 v71, v76, v77
	v_add_f32_e32 v74, v75, v74
	v_mul_f32_e32 v75, v81, v81
	v_mul_f32_e32 v76, v79, v79
	v_fmac_f32_e32 v75, v80, v80
	v_fmac_f32_e32 v76, v78, v78
	v_add_f32_e32 v75, v75, v76
	v_cvt_pk_bf16_f32 v72, v80, v81
	v_add_f32_e32 v80, v74, v75
	s_waitcnt vmcnt(6)
	v_lshlrev_b32_e32 v74, 16, v66
	v_and_b32_e32 v75, 0xffff0000, v66
	v_lshlrev_b32_e32 v66, 16, v67
	v_and_b32_e32 v67, 0xffff0000, v67
	v_pk_add_f32 v[76:77], v[108:109], v[66:67]
	v_pk_add_f32 v[66:67], v[106:107], v[74:75]
	v_lshlrev_b32_e32 v74, 16, v68
	v_and_b32_e32 v75, 0xffff0000, v68
	v_lshlrev_b32_e32 v68, 16, v69
	v_and_b32_e32 v69, 0xffff0000, v69
	v_cvt_pk_bf16_f32 v73, v78, v79
	v_pk_add_f32 v[78:79], v[104:105], v[68:69]
	v_mul_f32_e32 v68, v67, v67
	v_mul_f32_e32 v69, v77, v77
	v_pk_add_f32 v[74:75], v[102:103], v[74:75]
	v_fmac_f32_e32 v68, v66, v66
	v_fmac_f32_e32 v69, v76, v76
	v_add_f32_e32 v68, v68, v69
	v_mul_f32_e32 v69, v75, v75
	v_mul_f32_e32 v81, v79, v79
	v_fmac_f32_e32 v69, v74, v74
	v_fmac_f32_e32 v81, v78, v78
	v_add_f32_e32 v69, v69, v81
	v_add_f32_e32 v68, v68, v69
	v_add_f32_e32 v82, v80, v68
	ds_bpermute_b32 v83, v147, v82
	v_lshl_add_u64 v[68:69], s[86:87], 0, v[170:171]
	v_lshl_add_u64 v[80:81], v[148:149], 1, v[68:69]
	v_cvt_pk_bf16_f32 v68, v66, v67
	global_store_dwordx4 v[80:81], v[70:73], off sc1
	s_waitcnt lgkmcnt(0)
	v_add_f32_e32 v66, v82, v83
	ds_bpermute_b32 v67, v195, v66
	v_cvt_pk_bf16_f32 v69, v76, v77
	v_cvt_pk_bf16_f32 v70, v74, v75
	v_cvt_pk_bf16_f32 v71, v78, v79
	global_store_dwordx4 v[80:81], v[68:71], off offset:256 sc1
	s_and_saveexec_b64 s[44:45], s[6:7]
	s_cbranch_execz .LBB0_274
	v_lshl_add_u64 v[68:69], v[168:169], 2, s[48:49]
	s_waitcnt lgkmcnt(0)
	v_add_f32_e32 v66, v66, v67
	global_atomic_add_f32 v[68:69], v66, off
